# split-K finishers (w_o / w_ff2 sample rows): partial-tile and x loads of each row prefetched ahead of the add/store chain
# speedup vs baseline: 1.0789x; 1.0020x over previous
; __device__ __forceinline__ unsigned pk2(float lo, float hi) { unsigned r; asm volatile("v_cvt_pk_bf16_f32 %0, %1, %2" : "=v"(r) : "v"(lo), "v"(hi)); return r; }
;     ...
;         const int lane = threadIdx.x & 63, wv = threadIdx.x >> 6;
;         const int rbase = u.pm * 256 + (kq * 4 + u.pn) * 16 + wv * 2;
; #pragma unroll
;         for (int rr = 0; rr < 2; ++rr) {
;             const int row = rbase + rr; float sq = 0.f;
; #pragma unroll
;             for (int i = 0; i < 4; ++i) {
;                 const size_t o = (size_t)row * DM + i * 256 + lane * 4;
;                 f32x4 v = *(const f32x4*)(xold + o);
; #pragma unroll
;                 for (int q = 0; q < 4; ++q) v += *(const f32x4*)(part + (size_t)q * 1024 * DM + o);
;                 *(f32x4*)(xf_s + o) = v;
;                 u32x2 w; w.x = pk2(v[0], v[1]); w.y = pk2(v[2], v[3]); *(u32x2*)(xb_s + o) = w;
;                 sq += (v[0] * v[0] + v[1] * v[1]) + (v[2] * v[2] + v[3] * v[3]);
.LBB0_879:
	s_or_b64 exec, exec, s[10:11]
	s_add_u32 s22, s28, 0x4000000
	s_addc_u32 s23, s29, 0
	s_add_u32 s20, s20, 0x2000000
	s_addc_u32 s21, s21, 0
	s_lshr_b32 s8, s81, 2
	v_lshrrev_b32_e32 v0, 5, v166
	s_and_b32 s8, s8, 0xffffffc
	v_and_b32_e32 v0, 30, v0
	s_add_i32 s6, s6, s8
	v_lshl_or_b32 v0, s7, 8, v0
	v_lshl_add_u32 v2, s6, 4, v0
	v_ashrrev_i32_e32 v3, 31, v2
	v_lshlrev_b32_e32 v0, 2, v167
	v_lshlrev_b64 v[4:5], 10, v[2:3]
	v_or_b32_e32 v4, v4, v0
	v_lshlrev_b64 v[26:27], 2, v[4:5]
	v_lshl_add_u64 v[40:41], s[16:17], 0, v[26:27]
	s_mov_b32 s6, 0x400000
	v_add_co_u32_e32 v42, vcc, s6, v40
	s_mov_b32 s7, 0x800000
	s_nop 0
	v_addc_co_u32_e32 v43, vcc, 0, v41, vcc
	v_lshl_add_u64 v[38:39], s[14:15], 0, v[26:27]
	v_add_co_u32_e32 v44, vcc, s7, v40
	s_barrier
	global_load_dwordx4 v[6:9], v[38:39], off
	v_addc_co_u32_e32 v45, vcc, 0, v41, vcc
	s_mov_b32 s8, 0xc00000
	global_load_dwordx4 v[10:13], v[40:41], off
	global_load_dwordx4 v[14:17], v[42:43], off
	v_add_co_u32_e32 v46, vcc, s8, v40
	global_load_dwordx4 v[18:21], v[44:45], off
	s_nop 0
	v_addc_co_u32_e32 v47, vcc, 0, v41, vcc
	global_load_dwordx4 v[22:25], v[46:47], off
	v_lshl_add_u64 v[28:29], v[4:5], 1, s[20:21]
	v_lshl_add_u64 v[26:27], s[22:23], 0, v[26:27]
	v_mov_b32_e32 v31, v5
	v_or_b32_e32 v30, 0x100, v4
	v_lshl_add_u64 v[32:33], v[30:31], 2, s[22:23]
	v_lshl_add_u64 v[30:31], v[30:31], 1, s[20:21]
	v_mov_b32_e32 v35, v5
	v_or_b32_e32 v34, 0x200, v4
	v_lshl_add_u64 v[36:37], v[34:35], 2, s[22:23]
	v_lshl_add_u64 v[34:35], v[34:35], 1, s[20:21]
	v_mov_b32_e32 v1, 0
	v_or_b32_e32 v4, 0x300, v4
	s_mov_b64 s[24:25], 0x100000
	v_cmp_gt_u32_e64 s[10:11], 16, v167
	v_cmp_eq_u32_e32 vcc, 0, v167
	global_load_dwordx4 v[186:189], v[38:39], off offset:1024
	global_load_dwordx4 v[190:193], v[40:41], off offset:1024
	global_load_dwordx4 v[194:197], v[42:43], off offset:1024
	global_load_dwordx4 v[198:201], v[44:45], off offset:1024
	global_load_dwordx4 v[202:205], v[46:47], off offset:1024
	global_load_dwordx4 v[206:209], v[38:39], off offset:2048
	global_load_dwordx4 v[210:213], v[40:41], off offset:2048
	global_load_dwordx4 v[214:217], v[42:43], off offset:2048
	global_load_dwordx4 v[218:221], v[44:45], off offset:2048
	global_load_dwordx4 v[222:225], v[46:47], off offset:2048
	global_load_dwordx4 v[226:229], v[38:39], off offset:3072
	global_load_dwordx4 v[232:235], v[40:41], off offset:3072
	global_load_dwordx4 v[236:239], v[42:43], off offset:3072
	global_load_dwordx4 v[240:243], v[44:45], off offset:3072
	global_load_dwordx4 v[244:247], v[46:47], off offset:3072
	s_waitcnt vmcnt(18)
	v_pk_add_f32 v[8:9], v[8:9], v[12:13]
	v_pk_add_f32 v[6:7], v[6:7], v[10:11]
	s_waitcnt vmcnt(17)
	v_pk_add_f32 v[8:9], v[8:9], v[16:17]
	v_pk_add_f32 v[6:7], v[6:7], v[14:15]
	s_waitcnt vmcnt(16)
	v_pk_add_f32 v[8:9], v[8:9], v[20:21]
	v_pk_add_f32 v[6:7], v[6:7], v[18:19]
	s_waitcnt vmcnt(15)
	v_pk_add_f32 v[8:9], v[8:9], v[24:25]
	v_pk_add_f32 v[6:7], v[6:7], v[22:23]
	global_store_dwordx4 v[26:27], v[6:9], off
	v_cvt_pk_bf16_f32 v10, v6, v7
	v_cvt_pk_bf16_f32 v11, v8, v9
	global_store_dwordx2 v[28:29], v[10:11], off
	s_nop 0
	v_mul_f32_e32 v7, v7, v7
	v_mul_f32_e32 v9, v9, v9
	v_fmac_f32_e32 v7, v6, v6
	v_fmac_f32_e32 v9, v8, v8
	v_add_f32_e32 v6, v7, v9
	s_waitcnt vmcnt(12)
	v_mov_b32_e32 v10, v186
	v_mov_b32_e32 v11, v187
	v_mov_b32_e32 v12, v188
	v_mov_b32_e32 v13, v189
	v_mov_b32_e32 v14, v190
	v_mov_b32_e32 v15, v191
	v_mov_b32_e32 v16, v192
	v_mov_b32_e32 v17, v193
	v_mov_b32_e32 v18, v194
	v_mov_b32_e32 v19, v195
	v_mov_b32_e32 v20, v196
	v_mov_b32_e32 v21, v197
	v_mov_b32_e32 v22, v198
	v_mov_b32_e32 v23, v199
	v_mov_b32_e32 v24, v200
	v_mov_b32_e32 v25, v201
	v_mov_b32_e32 v26, v202
	v_mov_b32_e32 v27, v203
	v_mov_b32_e32 v28, v204
	v_mov_b32_e32 v29, v205
	v_pk_add_f32 v[12:13], v[12:13], v[16:17]
	v_pk_add_f32 v[10:11], v[10:11], v[14:15]
	v_pk_add_f32 v[12:13], v[12:13], v[20:21]
	v_pk_add_f32 v[10:11], v[10:11], v[18:19]
	v_pk_add_f32 v[12:13], v[12:13], v[24:25]
	v_pk_add_f32 v[10:11], v[10:11], v[22:23]
	v_pk_add_f32 v[12:13], v[12:13], v[28:29]
	v_pk_add_f32 v[10:11], v[10:11], v[26:27]
	global_store_dwordx4 v[32:33], v[10:13], off
	v_cvt_pk_bf16_f32 v14, v10, v11
	v_cvt_pk_bf16_f32 v15, v12, v13
	global_store_dwordx2 v[30:31], v[14:15], off
	s_nop 0
	v_mul_f32_e32 v7, v11, v11
	v_mul_f32_e32 v8, v13, v13
	v_fmac_f32_e32 v7, v10, v10
	v_fmac_f32_e32 v8, v12, v12
	v_add_f32_e32 v7, v7, v8
	v_add_f32_e32 v6, v6, v7
	s_waitcnt vmcnt(9)
	v_mov_b32_e32 v14, v206
	v_mov_b32_e32 v15, v207
	v_mov_b32_e32 v16, v208
	v_mov_b32_e32 v17, v209
	v_mov_b32_e32 v18, v210
	v_mov_b32_e32 v19, v211
	v_mov_b32_e32 v20, v212
	v_mov_b32_e32 v21, v213
	v_mov_b32_e32 v22, v214
	v_mov_b32_e32 v23, v215
	v_mov_b32_e32 v24, v216
	v_mov_b32_e32 v25, v217
	v_mov_b32_e32 v26, v218
	v_mov_b32_e32 v27, v219
	v_mov_b32_e32 v28, v220
	v_mov_b32_e32 v29, v221
	v_mov_b32_e32 v30, v222
	v_mov_b32_e32 v31, v223
	v_mov_b32_e32 v32, v224
	v_mov_b32_e32 v33, v225
	v_pk_add_f32 v[16:17], v[16:17], v[20:21]
	v_pk_add_f32 v[14:15], v[14:15], v[18:19]
	v_pk_add_f32 v[16:17], v[16:17], v[24:25]
	v_pk_add_f32 v[14:15], v[14:15], v[22:23]
	v_pk_add_f32 v[16:17], v[16:17], v[28:29]
	v_pk_add_f32 v[14:15], v[14:15], v[26:27]
	v_pk_add_f32 v[16:17], v[16:17], v[32:33]
	v_pk_add_f32 v[14:15], v[14:15], v[30:31]
	global_store_dwordx4 v[36:37], v[14:17], off
	v_cvt_pk_bf16_f32 v18, v14, v15
	v_cvt_pk_bf16_f32 v19, v16, v17
	global_store_dwordx2 v[34:35], v[18:19], off
	s_nop 0
	v_mul_f32_e32 v7, v15, v15
	v_mul_f32_e32 v8, v17, v17
	v_fmac_f32_e32 v7, v14, v14
	v_fmac_f32_e32 v8, v16, v16
	v_add_f32_e32 v7, v7, v8
	v_add_f32_e32 v10, v6, v7
	v_mbcnt_hi_u32_b32 v40, -1, v168
	v_lshl_add_u64 v[38:39], s[18:19], 0, v[0:1]
	v_and_b32_e32 v1, 64, v40
	v_xor_b32_e32 v41, 32, v40
	v_add_u32_e32 v44, 64, v1
	v_cmp_lt_i32_e64 s[12:13], v41, v44
	v_xor_b32_e32 v42, 16, v40
	v_xor_b32_e32 v43, 8, v40
	v_cndmask_b32_e64 v1, v40, v41, s[12:13]
	v_lshlrev_b32_e32 v1, 2, v1
	v_cmp_lt_i32_e64 s[12:13], v42, v44
	v_xor_b32_e32 v11, 2, v40
	v_xor_b32_e32 v12, 1, v40
	s_waitcnt vmcnt(6)
; __device__ __forceinline__ unsigned pk2(float lo, float hi) { unsigned r; asm volatile("v_cvt_pk_bf16_f32 %0, %1, %2" : "=v"(r) : "v"(lo), "v"(hi)); return r; }
;     ...
;         for (int rr = 0; rr < 2; ++rr) {
;             const int row = rbase + rr; float sq = 0.f;
; #pragma unroll
;             for (int i = 0; i < 4; ++i) {
;                 const size_t o = (size_t)row * DM + i * 256 + lane * 4;
;                 f32x4 v = *(const f32x4*)(xold + o);
; #pragma unroll
;                 for (int q = 0; q < 4; ++q) v += *(const f32x4*)(part + (size_t)q * 1024 * DM + o);
;                 *(f32x4*)(xf_s + o) = v;
;                 u32x2 w; w.x = pk2(v[0], v[1]); w.y = pk2(v[2], v[3]); *(u32x2*)(xb_s + o) = w;
;                 sq += (v[0] * v[0] + v[1] * v[1]) + (v[2] * v[2] + v[3] * v[3]);
;             }
; #pragma unroll
;             for (int o = 32; o >= 1; o >>= 1) sq += __shfl_xor(sq, o);
;             if (lane < 16) ssq_s[(size_t)row * 16 + lane] = lane == 0 ? sq : 0.f;
;         }
	v_mov_b32_e32 v18, v226
	v_mov_b32_e32 v19, v227
	v_mov_b32_e32 v20, v228
	v_mov_b32_e32 v21, v229
	v_mov_b32_e32 v22, v232
	v_mov_b32_e32 v23, v233
	v_mov_b32_e32 v24, v234
	v_mov_b32_e32 v25, v235
	v_mov_b32_e32 v26, v236
	v_mov_b32_e32 v27, v237
	v_mov_b32_e32 v28, v238
	v_mov_b32_e32 v29, v239
	v_mov_b32_e32 v30, v240
	v_mov_b32_e32 v31, v241
	v_mov_b32_e32 v32, v242
	v_mov_b32_e32 v33, v243
	v_mov_b32_e32 v34, v244
	v_mov_b32_e32 v35, v245
	v_mov_b32_e32 v36, v246
	v_mov_b32_e32 v37, v247
	v_pk_add_f32 v[6:7], v[20:21], v[24:25]
	v_pk_add_f32 v[8:9], v[18:19], v[22:23]
	v_pk_add_f32 v[6:7], v[6:7], v[28:29]
	v_pk_add_f32 v[8:9], v[8:9], v[26:27]
	v_pk_add_f32 v[6:7], v[6:7], v[32:33]
	v_pk_add_f32 v[8:9], v[8:9], v[30:31]
	v_pk_add_f32 v[18:19], v[6:7], v[36:37]
	v_pk_add_f32 v[16:17], v[8:9], v[34:35]
	v_mul_f32_e32 v7, v19, v19
	v_mul_f32_e32 v6, v17, v17
	v_fmac_f32_e32 v6, v16, v16
	v_fmac_f32_e32 v7, v18, v18
	v_add_f32_e32 v6, v6, v7
	v_add_f32_e32 v6, v10, v6
	ds_bpermute_b32 v7, v1, v6
	v_cndmask_b32_e64 v8, v40, v42, s[12:13]
	v_lshlrev_b32_e32 v8, 2, v8
	v_cmp_lt_i32_e64 s[12:13], v43, v44
	v_xor_b32_e32 v10, 4, v40
	s_waitcnt lgkmcnt(0)
	v_add_f32_e32 v6, v6, v7
	ds_bpermute_b32 v7, v8, v6
	v_cndmask_b32_e64 v9, v40, v43, s[12:13]
	v_lshlrev_b32_e32 v9, 2, v9
	v_cmp_lt_i32_e64 s[12:13], v10, v44
	s_waitcnt lgkmcnt(0)
	v_add_f32_e32 v6, v6, v7
	ds_bpermute_b32 v7, v9, v6
	v_cndmask_b32_e64 v10, v40, v10, s[12:13]
	v_lshlrev_b32_e32 v10, 2, v10
	v_cmp_lt_i32_e64 s[12:13], v11, v44
	s_waitcnt lgkmcnt(0)
	v_add_f32_e32 v13, v6, v7
	ds_bpermute_b32 v14, v10, v13
	v_cndmask_b32_e64 v11, v40, v11, s[12:13]
	v_lshlrev_b32_e32 v11, 2, v11
	v_cmp_lt_i32_e64 s[12:13], v12, v44
	v_lshl_add_u64 v[6:7], v[38:39], 0, s[24:25]
	s_waitcnt lgkmcnt(0)
	v_add_f32_e32 v14, v13, v14
	ds_bpermute_b32 v15, v11, v14
	v_cndmask_b32_e64 v20, v40, v12, s[12:13]
	v_lshl_add_u64 v[12:13], v[4:5], 2, s[22:23]
	global_store_dwordx4 v[12:13], v[16:19], off
	v_lshlrev_b32_e32 v12, 2, v20
	s_waitcnt lgkmcnt(0)
	v_add_f32_e32 v13, v14, v15
	ds_bpermute_b32 v14, v12, v13
	v_lshl_add_u64 v[4:5], v[4:5], 1, s[20:21]
	v_cvt_pk_bf16_f32 v16, v16, v17
	v_cvt_pk_bf16_f32 v17, v18, v19
	global_store_dwordx2 v[4:5], v[16:17], off
	s_and_saveexec_b64 s[12:13], s[10:11]
	s_cbranch_execz .LBB0_881
	v_lshlrev_b64 v[4:5], 6, v[2:3]
	s_waitcnt lgkmcnt(0)
	v_add_f32_e32 v3, v13, v14
	v_lshl_add_u64 v[4:5], v[6:7], 0, v[4:5]
	v_cndmask_b32_e32 v3, 0, v3, vcc
	global_store_dword v[4:5], v3, off
.LBB0_881:
	s_or_b64 exec, exec, s[12:13]
	v_or_b32_e32 v2, 1, v2
	v_ashrrev_i32_e32 v3, 31, v2
	v_lshlrev_b64 v[4:5], 10, v[2:3]
	v_or_b32_e32 v4, v4, v0
	v_lshlrev_b64 v[34:35], 2, v[4:5]
	v_lshl_add_u64 v[48:49], s[16:17], 0, v[34:35]
	v_add_co_u32_e64 v50, s[12:13], s6, v48
	v_lshl_add_u64 v[46:47], s[14:15], 0, v[34:35]
	s_nop 0
	v_addc_co_u32_e64 v51, s[12:13], 0, v49, s[12:13]
	v_add_co_u32_e64 v52, s[12:13], s7, v48
	s_waitcnt lgkmcnt(0)
	global_load_dwordx4 v[14:17], v[46:47], off
	v_addc_co_u32_e64 v53, s[12:13], 0, v49, s[12:13]
	global_load_dwordx4 v[18:21], v[48:49], off
	global_load_dwordx4 v[22:25], v[50:51], off
	v_add_co_u32_e64 v54, s[12:13], s8, v48
	global_load_dwordx4 v[26:29], v[52:53], off
	s_nop 0
	v_addc_co_u32_e64 v55, s[12:13], 0, v49, s[12:13]
	global_load_dwordx4 v[30:33], v[54:55], off
	v_lshl_add_u64 v[36:37], v[4:5], 1, s[20:21]
	v_lshl_add_u64 v[34:35], s[22:23], 0, v[34:35]
	v_mov_b32_e32 v39, v5
	v_or_b32_e32 v38, 0x100, v4
	v_lshl_add_u64 v[40:41], v[38:39], 2, s[22:23]
	v_lshl_add_u64 v[38:39], v[38:39], 1, s[20:21]
	v_mov_b32_e32 v43, v5
	v_or_b32_e32 v42, 0x200, v4
	v_lshl_add_u64 v[44:45], v[42:43], 2, s[22:23]
	v_lshl_add_u64 v[42:43], v[42:43], 1, s[20:21]
	v_or_b32_e32 v4, 0x300, v4
	global_load_dwordx4 v[186:189], v[46:47], off offset:1024
	global_load_dwordx4 v[190:193], v[48:49], off offset:1024
	global_load_dwordx4 v[194:197], v[50:51], off offset:1024
	global_load_dwordx4 v[198:201], v[52:53], off offset:1024
	global_load_dwordx4 v[202:205], v[54:55], off offset:1024
	global_load_dwordx4 v[206:209], v[46:47], off offset:2048
	global_load_dwordx4 v[210:213], v[48:49], off offset:2048
	global_load_dwordx4 v[214:217], v[50:51], off offset:2048
	global_load_dwordx4 v[218:221], v[52:53], off offset:2048
	global_load_dwordx4 v[222:225], v[54:55], off offset:2048
	global_load_dwordx4 v[226:229], v[46:47], off offset:3072
	global_load_dwordx4 v[232:235], v[48:49], off offset:3072
	global_load_dwordx4 v[236:239], v[50:51], off offset:3072
	global_load_dwordx4 v[240:243], v[52:53], off offset:3072
	global_load_dwordx4 v[244:247], v[54:55], off offset:3072
	s_waitcnt vmcnt(18)
	v_pk_add_f32 v[16:17], v[16:17], v[20:21]
	v_pk_add_f32 v[14:15], v[14:15], v[18:19]
	s_waitcnt vmcnt(17)
	v_pk_add_f32 v[16:17], v[16:17], v[24:25]
	v_pk_add_f32 v[14:15], v[14:15], v[22:23]
	s_waitcnt vmcnt(16)
; __device__ __forceinline__ unsigned pk2(float lo, float hi) { unsigned r; asm volatile("v_cvt_pk_bf16_f32 %0, %1, %2" : "=v"(r) : "v"(lo), "v"(hi)); return r; }
;     ...
;             for (int i = 0; i < 4; ++i) {
;                 const size_t o = (size_t)row * DM + i * 256 + lane * 4;
;                 f32x4 v = *(const f32x4*)(xold + o);
; #pragma unroll
;                 for (int q = 0; q < 4; ++q) v += *(const f32x4*)(part + (size_t)q * 1024 * DM + o);
;                 *(f32x4*)(xf_s + o) = v;
;                 u32x2 w; w.x = pk2(v[0], v[1]); w.y = pk2(v[2], v[3]); *(u32x2*)(xb_s + o) = w;
;                 sq += (v[0] * v[0] + v[1] * v[1]) + (v[2] * v[2] + v[3] * v[3]);
;             }
; #pragma unroll
;             for (int o = 32; o >= 1; o >>= 1) sq += __shfl_xor(sq, o);
;             if (lane < 16) ssq_s[(size_t)row * 16 + lane] = lane == 0 ? sq : 0.f;
;         }
	v_pk_add_f32 v[16:17], v[16:17], v[28:29]
	v_pk_add_f32 v[14:15], v[14:15], v[26:27]
	s_waitcnt vmcnt(15)
	v_pk_add_f32 v[16:17], v[16:17], v[32:33]
	v_pk_add_f32 v[14:15], v[14:15], v[30:31]
	global_store_dwordx4 v[34:35], v[14:17], off
	v_cvt_pk_bf16_f32 v18, v14, v15
	v_cvt_pk_bf16_f32 v19, v16, v17
	global_store_dwordx2 v[36:37], v[18:19], off
	s_nop 0
	v_mul_f32_e32 v0, v15, v15
	v_mul_f32_e32 v13, v17, v17
	v_fmac_f32_e32 v0, v14, v14
	v_fmac_f32_e32 v13, v16, v16
	v_add_f32_e32 v0, v0, v13
	s_waitcnt vmcnt(12)
	v_mov_b32_e32 v18, v186
	v_mov_b32_e32 v19, v187
	v_mov_b32_e32 v20, v188
	v_mov_b32_e32 v21, v189
	v_mov_b32_e32 v22, v190
	v_mov_b32_e32 v23, v191
	v_mov_b32_e32 v24, v192
	v_mov_b32_e32 v25, v193
	v_mov_b32_e32 v26, v194
	v_mov_b32_e32 v27, v195
	v_mov_b32_e32 v28, v196
	v_mov_b32_e32 v29, v197
	v_mov_b32_e32 v30, v198
	v_mov_b32_e32 v31, v199
	v_mov_b32_e32 v32, v200
	v_mov_b32_e32 v33, v201
	v_mov_b32_e32 v34, v202
	v_mov_b32_e32 v35, v203
	v_mov_b32_e32 v36, v204
	v_mov_b32_e32 v37, v205
	v_pk_add_f32 v[20:21], v[20:21], v[24:25]
	v_pk_add_f32 v[18:19], v[18:19], v[22:23]
	v_pk_add_f32 v[20:21], v[20:21], v[28:29]
	v_pk_add_f32 v[18:19], v[18:19], v[26:27]
	v_pk_add_f32 v[20:21], v[20:21], v[32:33]
	v_pk_add_f32 v[18:19], v[18:19], v[30:31]
	v_pk_add_f32 v[20:21], v[20:21], v[36:37]
	v_pk_add_f32 v[18:19], v[18:19], v[34:35]
	global_store_dwordx4 v[40:41], v[18:21], off
	v_cvt_pk_bf16_f32 v22, v18, v19
	v_cvt_pk_bf16_f32 v23, v20, v21
	global_store_dwordx2 v[38:39], v[22:23], off
	s_nop 0
	v_mul_f32_e32 v13, v19, v19
	v_mul_f32_e32 v14, v21, v21
	v_fmac_f32_e32 v13, v18, v18
	v_fmac_f32_e32 v14, v20, v20
	v_add_f32_e32 v13, v13, v14
	v_add_f32_e32 v0, v0, v13
	s_waitcnt vmcnt(9)
	v_mov_b32_e32 v22, v206
	v_mov_b32_e32 v23, v207
	v_mov_b32_e32 v24, v208
	v_mov_b32_e32 v25, v209
	v_mov_b32_e32 v26, v210
	v_mov_b32_e32 v27, v211
	v_mov_b32_e32 v28, v212
	v_mov_b32_e32 v29, v213
	v_mov_b32_e32 v30, v214
	v_mov_b32_e32 v31, v215
	v_mov_b32_e32 v32, v216
	v_mov_b32_e32 v33, v217
	v_mov_b32_e32 v34, v218
	v_mov_b32_e32 v35, v219
	v_mov_b32_e32 v36, v220
	v_mov_b32_e32 v37, v221
	v_mov_b32_e32 v38, v222
	v_mov_b32_e32 v39, v223
	v_mov_b32_e32 v40, v224
	v_mov_b32_e32 v41, v225
	v_pk_add_f32 v[24:25], v[24:25], v[28:29]
	v_pk_add_f32 v[22:23], v[22:23], v[26:27]
	v_pk_add_f32 v[24:25], v[24:25], v[32:33]
	v_pk_add_f32 v[22:23], v[22:23], v[30:31]
	v_pk_add_f32 v[24:25], v[24:25], v[36:37]
	v_pk_add_f32 v[22:23], v[22:23], v[34:35]
	v_pk_add_f32 v[24:25], v[24:25], v[40:41]
	v_pk_add_f32 v[22:23], v[22:23], v[38:39]
	global_store_dwordx4 v[44:45], v[22:25], off
	v_cvt_pk_bf16_f32 v26, v22, v23
	v_cvt_pk_bf16_f32 v27, v24, v25
	global_store_dwordx2 v[42:43], v[26:27], off
	s_nop 0
	v_mul_f32_e32 v13, v23, v23
	v_mul_f32_e32 v14, v25, v25
	v_fmac_f32_e32 v13, v22, v22
	v_fmac_f32_e32 v14, v24, v24
	v_add_f32_e32 v13, v13, v14
	v_add_f32_e32 v0, v0, v13
	s_waitcnt vmcnt(6)
	v_mov_b32_e32 v26, v226
	v_mov_b32_e32 v27, v227
	v_mov_b32_e32 v28, v228
	v_mov_b32_e32 v29, v229
	v_mov_b32_e32 v30, v232
	v_mov_b32_e32 v31, v233
	v_mov_b32_e32 v32, v234
	v_mov_b32_e32 v33, v235
	v_mov_b32_e32 v34, v236
	v_mov_b32_e32 v35, v237
	v_mov_b32_e32 v36, v238
	v_mov_b32_e32 v37, v239
	v_mov_b32_e32 v38, v240
	v_mov_b32_e32 v39, v241
	v_mov_b32_e32 v40, v242
	v_mov_b32_e32 v41, v243
	v_mov_b32_e32 v42, v244
	v_mov_b32_e32 v43, v245
	v_mov_b32_e32 v44, v246
	v_mov_b32_e32 v45, v247
	v_pk_add_f32 v[14:15], v[28:29], v[32:33]
	v_pk_add_f32 v[16:17], v[26:27], v[30:31]
	v_pk_add_f32 v[14:15], v[14:15], v[36:37]
	v_pk_add_f32 v[16:17], v[16:17], v[34:35]
	v_pk_add_f32 v[14:15], v[14:15], v[40:41]
	v_pk_add_f32 v[18:19], v[16:17], v[38:39]
	v_pk_add_f32 v[16:17], v[14:15], v[44:45]
	v_pk_add_f32 v[14:15], v[18:19], v[42:43]
	v_mul_f32_e32 v18, v17, v17
	v_mul_f32_e32 v13, v15, v15
	v_fmac_f32_e32 v13, v14, v14
	v_fmac_f32_e32 v18, v16, v16
	v_add_f32_e32 v13, v13, v18
	v_add_f32_e32 v0, v0, v13
	ds_bpermute_b32 v1, v1, v0
	s_waitcnt lgkmcnt(0)
	v_add_f32_e32 v0, v0, v1
	ds_bpermute_b32 v1, v8, v0
	s_waitcnt lgkmcnt(0)
	v_add_f32_e32 v0, v0, v1
	ds_bpermute_b32 v1, v9, v0
	s_waitcnt lgkmcnt(0)
	v_add_f32_e32 v0, v0, v1
	ds_bpermute_b32 v1, v10, v0
	s_waitcnt lgkmcnt(0)
	v_add_f32_e32 v8, v0, v1
	ds_bpermute_b32 v9, v11, v8
	v_lshl_add_u64 v[0:1], v[4:5], 2, s[22:23]
	global_store_dwordx4 v[0:1], v[14:17], off
	v_lshl_add_u64 v[4:5], v[4:5], 1, s[20:21]
	s_waitcnt lgkmcnt(0)
	v_add_f32_e32 v0, v8, v9
	ds_bpermute_b32 v1, v12, v0
	v_cvt_pk_bf16_f32 v8, v14, v15
	v_cvt_pk_bf16_f32 v9, v16, v17
	global_store_dwordx2 v[4:5], v[8:9], off
	s_and_saveexec_b64 s[12:13], s[10:11]
	s_cbranch_execz .LBB0_883
	v_lshlrev_b64 v[2:3], 6, v[2:3]
	s_waitcnt lgkmcnt(0)
	v_add_f32_e32 v0, v0, v1
	v_lshl_add_u64 v[2:3], v[6:7], 0, v[2:3]
	v_cndmask_b32_e32 v0, 0, v0, vcc
	global_store_dword v[2:3], v0, off

; __device__ __forceinline__ unsigned pk2(float lo, float hi) { unsigned r; asm volatile("v_cvt_pk_bf16_f32 %0, %1, %2" : "=v"(r) : "v"(lo), "v"(hi)); return r; }
;     ...
;         const int lane = threadIdx.x & 63, wv = threadIdx.x >> 6;
;         const int rbase = u.pm * 256 + (kq * 4 + u.pn) * 16 + wv * 2;
; #pragma unroll
;         for (int rr = 0; rr < 2; ++rr) {
;             const int row = rbase + rr; float sq = 0.f;
; #pragma unroll
;             for (int i = 0; i < 4; ++i) {
;                 const size_t o = (size_t)row * DM + i * 256 + lane * 4;
;                 f32x4 v = *(const f32x4*)(xold + o);
; #pragma unroll
;                 for (int q = 0; q < 4; ++q) v += *(const f32x4*)(part + (size_t)q * 1024 * DM + o);
;                 *(f32x4*)(xf_s + o) = v;
;                 u32x2 w; w.x = pk2(v[0], v[1]); w.y = pk2(v[2], v[3]); *(u32x2*)(xb_s + o) = w;
;                 sq += (v[0] * v[0] + v[1] * v[1]) + (v[2] * v[2] + v[3] * v[3]);
.LBB0_1154:
	s_or_b64 exec, exec, s[10:11]
	s_add_u32 s18, s20, 0x4000000
	s_addc_u32 s19, s21, 0
	s_add_u32 s16, s16, 0x2000000
	s_addc_u32 s17, s17, 0
	s_lshr_b32 s8, s70, 2
	v_lshrrev_b32_e32 v0, 5, v166
	s_and_b32 s8, s8, 0xffffffc
	v_and_b32_e32 v0, 30, v0
	s_add_i32 s6, s6, s8
	v_lshl_or_b32 v0, s7, 8, v0
	v_lshl_add_u32 v2, s6, 4, v0
	v_ashrrev_i32_e32 v3, 31, v2
	v_lshlrev_b32_e32 v0, 2, v167
	v_lshlrev_b64 v[4:5], 10, v[2:3]
	v_or_b32_e32 v4, v4, v0
	v_lshlrev_b64 v[10:11], 2, v[4:5]
	v_lshl_add_u64 v[38:39], s[14:15], 0, v[10:11]
	s_mov_b32 s6, 0x400000
	v_add_co_u32_e32 v40, vcc, s6, v38
	s_mov_b32 s7, 0x800000
	s_nop 0
	v_addc_co_u32_e32 v41, vcc, 0, v39, vcc
	v_lshl_add_u64 v[26:27], s[18:19], 0, v[10:11]
	v_add_co_u32_e32 v42, vcc, s7, v38
	s_barrier
	global_load_dwordx4 v[6:9], v[26:27], off
	v_addc_co_u32_e32 v43, vcc, 0, v39, vcc
	s_mov_b32 s8, 0xc00000
	global_load_dwordx4 v[10:13], v[38:39], off
	global_load_dwordx4 v[14:17], v[40:41], off
	v_add_co_u32_e32 v44, vcc, s8, v38
	global_load_dwordx4 v[18:21], v[42:43], off
	s_nop 0
	v_addc_co_u32_e32 v45, vcc, 0, v39, vcc
	global_load_dwordx4 v[22:25], v[44:45], off
	v_mov_b32_e32 v31, v5
	v_lshl_add_u64 v[28:29], v[4:5], 1, s[16:17]
	v_or_b32_e32 v30, 0x100, v4
	v_lshl_add_u64 v[32:33], v[30:31], 2, s[18:19]
	v_mov_b32_e32 v35, v5
	v_or_b32_e32 v34, 0x200, v4
	v_lshl_add_u64 v[30:31], v[30:31], 1, s[16:17]
	v_lshl_add_u64 v[36:37], v[34:35], 2, s[18:19]
	v_or_b32_e32 v4, 0x300, v4
	v_lshl_add_u64 v[34:35], v[34:35], 1, s[16:17]
	v_lshl_add_u64 v[46:47], v[4:5], 2, s[18:19]
	v_mov_b32_e32 v1, 0
	s_mov_b64 s[20:21], 0x100000
	v_cmp_gt_u32_e64 s[10:11], 16, v167
	v_cmp_eq_u32_e32 vcc, 0, v167
	v_lshl_add_u64 v[4:5], v[4:5], 1, s[16:17]
	global_load_dwordx4 v[186:189], v[32:33], off
	global_load_dwordx4 v[190:193], v[38:39], off offset:1024
	global_load_dwordx4 v[194:197], v[40:41], off offset:1024
	global_load_dwordx4 v[198:201], v[42:43], off offset:1024
	global_load_dwordx4 v[202:205], v[44:45], off offset:1024
	global_load_dwordx4 v[206:209], v[36:37], off
	global_load_dwordx4 v[210:213], v[38:39], off offset:2048
	global_load_dwordx4 v[214:217], v[40:41], off offset:2048
	global_load_dwordx4 v[218:221], v[42:43], off offset:2048
	global_load_dwordx4 v[222:225], v[44:45], off offset:2048
	global_load_dwordx4 v[226:229], v[46:47], off
	global_load_dwordx4 v[232:235], v[38:39], off offset:3072
	global_load_dwordx4 v[236:239], v[40:41], off offset:3072
	global_load_dwordx4 v[240:243], v[42:43], off offset:3072
	global_load_dwordx4 v[244:247], v[44:45], off offset:3072
	s_waitcnt vmcnt(18)
	v_pk_add_f32 v[8:9], v[8:9], v[12:13]
	v_pk_add_f32 v[6:7], v[6:7], v[10:11]
	s_waitcnt vmcnt(17)
	v_pk_add_f32 v[8:9], v[8:9], v[16:17]
	v_pk_add_f32 v[6:7], v[6:7], v[14:15]
	s_waitcnt vmcnt(16)
	v_pk_add_f32 v[8:9], v[8:9], v[20:21]
	v_pk_add_f32 v[6:7], v[6:7], v[18:19]
	s_waitcnt vmcnt(15)
	v_pk_add_f32 v[8:9], v[8:9], v[24:25]
	v_pk_add_f32 v[6:7], v[6:7], v[22:23]
	global_store_dwordx4 v[26:27], v[6:9], off
	v_cvt_pk_bf16_f32 v10, v6, v7
	v_cvt_pk_bf16_f32 v11, v8, v9
	global_store_dwordx2 v[28:29], v[10:11], off
	s_nop 0
	v_mul_f32_e32 v7, v7, v7
	v_mul_f32_e32 v9, v9, v9
	v_fmac_f32_e32 v7, v6, v6
	v_fmac_f32_e32 v9, v8, v8
	v_add_f32_e32 v6, v7, v9
	s_waitcnt vmcnt(12)
	v_mov_b32_e32 v10, v186
	v_mov_b32_e32 v11, v187
	v_mov_b32_e32 v12, v188
	v_mov_b32_e32 v13, v189
	v_mov_b32_e32 v14, v190
	v_mov_b32_e32 v15, v191
	v_mov_b32_e32 v16, v192
	v_mov_b32_e32 v17, v193
	v_mov_b32_e32 v18, v194
	v_mov_b32_e32 v19, v195
	v_mov_b32_e32 v20, v196
	v_mov_b32_e32 v21, v197
	v_mov_b32_e32 v22, v198
	v_mov_b32_e32 v23, v199
	v_mov_b32_e32 v24, v200
	v_mov_b32_e32 v25, v201
	v_mov_b32_e32 v26, v202
	v_mov_b32_e32 v27, v203
	v_mov_b32_e32 v28, v204
	v_mov_b32_e32 v29, v205
	v_pk_add_f32 v[12:13], v[12:13], v[16:17]
	v_pk_add_f32 v[10:11], v[10:11], v[14:15]
	v_pk_add_f32 v[12:13], v[12:13], v[20:21]
	v_pk_add_f32 v[10:11], v[10:11], v[18:19]
	v_pk_add_f32 v[12:13], v[12:13], v[24:25]
	v_pk_add_f32 v[10:11], v[10:11], v[22:23]
	v_pk_add_f32 v[12:13], v[12:13], v[28:29]
	v_pk_add_f32 v[10:11], v[10:11], v[26:27]
	global_store_dwordx4 v[32:33], v[10:13], off
	v_cvt_pk_bf16_f32 v14, v10, v11
	v_cvt_pk_bf16_f32 v15, v12, v13
	global_store_dwordx2 v[30:31], v[14:15], off
	s_nop 0
	v_mul_f32_e32 v7, v11, v11
	v_mul_f32_e32 v8, v13, v13
	v_fmac_f32_e32 v7, v10, v10
	v_fmac_f32_e32 v8, v12, v12
	v_add_f32_e32 v7, v7, v8
	v_add_f32_e32 v6, v6, v7
	s_waitcnt vmcnt(9)
	v_mov_b32_e32 v14, v206
	v_mov_b32_e32 v15, v207
	v_mov_b32_e32 v16, v208
	v_mov_b32_e32 v17, v209
	v_mov_b32_e32 v18, v210
	v_mov_b32_e32 v19, v211
	v_mov_b32_e32 v20, v212
	v_mov_b32_e32 v21, v213
	v_mov_b32_e32 v22, v214
	v_mov_b32_e32 v23, v215
	v_mov_b32_e32 v24, v216
	v_mov_b32_e32 v25, v217
	v_mov_b32_e32 v26, v218
	v_mov_b32_e32 v27, v219
	v_mov_b32_e32 v28, v220
	v_mov_b32_e32 v29, v221
	v_mov_b32_e32 v30, v222
	v_mov_b32_e32 v31, v223
	v_mov_b32_e32 v32, v224
	v_mov_b32_e32 v33, v225
	v_pk_add_f32 v[16:17], v[16:17], v[20:21]
	v_pk_add_f32 v[14:15], v[14:15], v[18:19]
	v_pk_add_f32 v[16:17], v[16:17], v[24:25]
	v_pk_add_f32 v[14:15], v[14:15], v[22:23]
	v_pk_add_f32 v[16:17], v[16:17], v[28:29]
	v_pk_add_f32 v[14:15], v[14:15], v[26:27]
	v_pk_add_f32 v[16:17], v[16:17], v[32:33]
	v_pk_add_f32 v[14:15], v[14:15], v[30:31]
	global_store_dwordx4 v[36:37], v[14:17], off
	v_cvt_pk_bf16_f32 v18, v14, v15
	v_cvt_pk_bf16_f32 v19, v16, v17
	global_store_dwordx2 v[34:35], v[18:19], off
	s_nop 0
	v_mul_f32_e32 v7, v15, v15
	v_mul_f32_e32 v8, v17, v17
	v_fmac_f32_e32 v7, v14, v14
	v_fmac_f32_e32 v8, v16, v16
	v_add_f32_e32 v7, v7, v8
	v_add_f32_e32 v10, v6, v7
	v_mbcnt_hi_u32_b32 v40, -1, v168
	v_lshl_add_u64 v[38:39], s[12:13], 0, v[0:1]
	v_and_b32_e32 v1, 64, v40
	v_xor_b32_e32 v41, 32, v40
	v_add_u32_e32 v43, 64, v1
	v_cmp_lt_i32_e64 s[12:13], v41, v43
	v_xor_b32_e32 v42, 16, v40
	v_xor_b32_e32 v11, 2, v40
	v_cndmask_b32_e64 v1, v40, v41, s[12:13]
	v_lshlrev_b32_e32 v1, 2, v1
	v_cmp_lt_i32_e64 s[12:13], v42, v43
	v_xor_b32_e32 v12, 1, v40
	s_waitcnt vmcnt(6)
; __device__ __forceinline__ unsigned pk2(float lo, float hi) { unsigned r; asm volatile("v_cvt_pk_bf16_f32 %0, %1, %2" : "=v"(r) : "v"(lo), "v"(hi)); return r; }
;     ...
;         for (int rr = 0; rr < 2; ++rr) {
;             const int row = rbase + rr; float sq = 0.f;
; #pragma unroll
;             for (int i = 0; i < 4; ++i) {
;                 const size_t o = (size_t)row * DM + i * 256 + lane * 4;
;                 f32x4 v = *(const f32x4*)(xold + o);
; #pragma unroll
;                 for (int q = 0; q < 4; ++q) v += *(const f32x4*)(part + (size_t)q * 1024 * DM + o);
;                 *(f32x4*)(xf_s + o) = v;
;                 u32x2 w; w.x = pk2(v[0], v[1]); w.y = pk2(v[2], v[3]); *(u32x2*)(xb_s + o) = w;
;                 sq += (v[0] * v[0] + v[1] * v[1]) + (v[2] * v[2] + v[3] * v[3]);
;             }
; #pragma unroll
;             for (int o = 32; o >= 1; o >>= 1) sq += __shfl_xor(sq, o);
;             if (lane < 16) ssq_s[(size_t)row * 16 + lane] = lane == 0 ? sq : 0.f;
;         }
	v_mov_b32_e32 v18, v226
	v_mov_b32_e32 v19, v227
	v_mov_b32_e32 v20, v228
	v_mov_b32_e32 v21, v229
	v_mov_b32_e32 v22, v232
	v_mov_b32_e32 v23, v233
	v_mov_b32_e32 v24, v234
	v_mov_b32_e32 v25, v235
	v_mov_b32_e32 v26, v236
	v_mov_b32_e32 v27, v237
	v_mov_b32_e32 v28, v238
	v_mov_b32_e32 v29, v239
	v_mov_b32_e32 v30, v240
	v_mov_b32_e32 v31, v241
	v_mov_b32_e32 v32, v242
	v_mov_b32_e32 v33, v243
	v_mov_b32_e32 v34, v244
	v_mov_b32_e32 v35, v245
	v_mov_b32_e32 v36, v246
	v_mov_b32_e32 v37, v247
	v_pk_add_f32 v[6:7], v[20:21], v[24:25]
	v_pk_add_f32 v[8:9], v[18:19], v[22:23]
	v_pk_add_f32 v[6:7], v[6:7], v[28:29]
	v_pk_add_f32 v[8:9], v[8:9], v[26:27]
	v_pk_add_f32 v[6:7], v[6:7], v[32:33]
	v_pk_add_f32 v[8:9], v[8:9], v[30:31]
	v_pk_add_f32 v[18:19], v[6:7], v[36:37]
	v_pk_add_f32 v[16:17], v[8:9], v[34:35]
	v_mul_f32_e32 v7, v19, v19
	v_mul_f32_e32 v6, v17, v17
	v_fmac_f32_e32 v6, v16, v16
	v_fmac_f32_e32 v7, v18, v18
	v_add_f32_e32 v6, v6, v7
	v_add_f32_e32 v6, v10, v6
	ds_bpermute_b32 v7, v1, v6
	v_cndmask_b32_e64 v8, v40, v42, s[12:13]
	v_lshlrev_b32_e32 v8, 2, v8
	v_xor_b32_e32 v9, 8, v40
	v_cmp_lt_i32_e64 s[12:13], v9, v43
	s_waitcnt lgkmcnt(0)
	v_add_f32_e32 v6, v6, v7
	ds_bpermute_b32 v7, v8, v6
	v_cndmask_b32_e64 v9, v40, v9, s[12:13]
	v_lshlrev_b32_e32 v9, 2, v9
	v_xor_b32_e32 v10, 4, v40
	v_cmp_lt_i32_e64 s[12:13], v10, v43
	s_waitcnt lgkmcnt(0)
	v_add_f32_e32 v6, v6, v7
	ds_bpermute_b32 v7, v9, v6
	v_cndmask_b32_e64 v10, v40, v10, s[12:13]
	v_lshlrev_b32_e32 v10, 2, v10
	v_cmp_lt_i32_e64 s[12:13], v11, v43
	global_store_dwordx4 v[46:47], v[16:19], off
	s_waitcnt lgkmcnt(0)
	v_add_f32_e32 v6, v6, v7
	ds_bpermute_b32 v7, v10, v6
	v_cndmask_b32_e64 v11, v40, v11, s[12:13]
	v_lshlrev_b32_e32 v11, 2, v11
	v_cmp_lt_i32_e64 s[12:13], v12, v43
	v_cvt_pk_bf16_f32 v16, v16, v17
	s_waitcnt lgkmcnt(0)
	v_add_f32_e32 v13, v6, v7
	ds_bpermute_b32 v14, v11, v13
	v_cndmask_b32_e64 v12, v40, v12, s[12:13]
	v_lshlrev_b32_e32 v12, 2, v12
	v_lshl_add_u64 v[6:7], v[38:39], 0, s[20:21]
	v_cvt_pk_bf16_f32 v17, v18, v19
	s_waitcnt lgkmcnt(0)
	v_add_f32_e32 v13, v13, v14
	ds_bpermute_b32 v14, v12, v13
	global_store_dwordx2 v[4:5], v[16:17], off
	s_and_saveexec_b64 s[12:13], s[10:11]
	s_cbranch_execz .LBB0_1156
	v_lshlrev_b64 v[4:5], 6, v[2:3]
	s_waitcnt lgkmcnt(0)
	v_add_f32_e32 v3, v13, v14
	v_lshl_add_u64 v[4:5], v[6:7], 0, v[4:5]
	v_cndmask_b32_e32 v3, 0, v3, vcc
	global_store_dword v[4:5], v3, off
.LBB0_1156:
	s_or_b64 exec, exec, s[12:13]
	v_or_b32_e32 v2, 1, v2
	v_ashrrev_i32_e32 v3, 31, v2
	v_lshlrev_b64 v[4:5], 10, v[2:3]
	v_or_b32_e32 v4, v4, v0
	v_lshlrev_b64 v[18:19], 2, v[4:5]
	v_lshl_add_u64 v[46:47], s[14:15], 0, v[18:19]
	v_add_co_u32_e64 v48, s[12:13], s6, v46
	v_lshl_add_u64 v[34:35], s[18:19], 0, v[18:19]
	s_nop 0
	v_addc_co_u32_e64 v49, s[12:13], 0, v47, s[12:13]
	v_add_co_u32_e64 v50, s[12:13], s7, v46
	s_waitcnt lgkmcnt(0)
	global_load_dwordx4 v[14:17], v[34:35], off
	v_addc_co_u32_e64 v51, s[12:13], 0, v47, s[12:13]
	global_load_dwordx4 v[18:21], v[46:47], off
	global_load_dwordx4 v[22:25], v[48:49], off
	v_add_co_u32_e64 v52, s[12:13], s8, v46
	global_load_dwordx4 v[26:29], v[50:51], off
	s_nop 0
	v_addc_co_u32_e64 v53, s[12:13], 0, v47, s[12:13]
	global_load_dwordx4 v[30:33], v[52:53], off
	v_mov_b32_e32 v39, v5
	v_lshl_add_u64 v[36:37], v[4:5], 1, s[16:17]
	v_or_b32_e32 v38, 0x100, v4
	v_lshl_add_u64 v[40:41], v[38:39], 2, s[18:19]
	v_mov_b32_e32 v43, v5
	v_or_b32_e32 v42, 0x200, v4
	v_lshl_add_u64 v[38:39], v[38:39], 1, s[16:17]
	v_lshl_add_u64 v[44:45], v[42:43], 2, s[18:19]
	v_or_b32_e32 v4, 0x300, v4
	v_lshl_add_u64 v[42:43], v[42:43], 1, s[16:17]
	v_lshl_add_u64 v[54:55], v[4:5], 2, s[18:19]
	v_lshl_add_u64 v[4:5], v[4:5], 1, s[16:17]
	global_load_dwordx4 v[186:189], v[40:41], off
	global_load_dwordx4 v[190:193], v[46:47], off offset:1024
	global_load_dwordx4 v[194:197], v[48:49], off offset:1024
	global_load_dwordx4 v[198:201], v[50:51], off offset:1024
	global_load_dwordx4 v[202:205], v[52:53], off offset:1024
	global_load_dwordx4 v[206:209], v[44:45], off
	global_load_dwordx4 v[210:213], v[46:47], off offset:2048
	global_load_dwordx4 v[214:217], v[48:49], off offset:2048
	global_load_dwordx4 v[218:221], v[50:51], off offset:2048
	global_load_dwordx4 v[222:225], v[52:53], off offset:2048
	global_load_dwordx4 v[226:229], v[54:55], off
	global_load_dwordx4 v[232:235], v[46:47], off offset:3072
	global_load_dwordx4 v[236:239], v[48:49], off offset:3072
	global_load_dwordx4 v[240:243], v[50:51], off offset:3072
	global_load_dwordx4 v[244:247], v[52:53], off offset:3072
	s_waitcnt vmcnt(18)
	v_pk_add_f32 v[16:17], v[16:17], v[20:21]
	v_pk_add_f32 v[14:15], v[14:15], v[18:19]
	s_waitcnt vmcnt(17)
	v_pk_add_f32 v[16:17], v[16:17], v[24:25]
	v_pk_add_f32 v[14:15], v[14:15], v[22:23]
	s_waitcnt vmcnt(16)
; __device__ __forceinline__ unsigned pk2(float lo, float hi) { unsigned r; asm volatile("v_cvt_pk_bf16_f32 %0, %1, %2" : "=v"(r) : "v"(lo), "v"(hi)); return r; }
;     ...
;             for (int i = 0; i < 4; ++i) {
;                 const size_t o = (size_t)row * DM + i * 256 + lane * 4;
;                 f32x4 v = *(const f32x4*)(xold + o);
; #pragma unroll
;                 for (int q = 0; q < 4; ++q) v += *(const f32x4*)(part + (size_t)q * 1024 * DM + o);
;                 *(f32x4*)(xf_s + o) = v;
;                 u32x2 w; w.x = pk2(v[0], v[1]); w.y = pk2(v[2], v[3]); *(u32x2*)(xb_s + o) = w;
;                 sq += (v[0] * v[0] + v[1] * v[1]) + (v[2] * v[2] + v[3] * v[3]);
;             }
; #pragma unroll
;             for (int o = 32; o >= 1; o >>= 1) sq += __shfl_xor(sq, o);
;             if (lane < 16) ssq_s[(size_t)row * 16 + lane] = lane == 0 ? sq : 0.f;
;         }
	v_pk_add_f32 v[16:17], v[16:17], v[28:29]
	v_pk_add_f32 v[14:15], v[14:15], v[26:27]
	s_waitcnt vmcnt(15)
	v_pk_add_f32 v[16:17], v[16:17], v[32:33]
	v_pk_add_f32 v[14:15], v[14:15], v[30:31]
	global_store_dwordx4 v[34:35], v[14:17], off
	v_cvt_pk_bf16_f32 v18, v14, v15
	v_cvt_pk_bf16_f32 v19, v16, v17
	global_store_dwordx2 v[36:37], v[18:19], off
	s_nop 0
	v_mul_f32_e32 v0, v15, v15
	v_mul_f32_e32 v13, v17, v17
	v_fmac_f32_e32 v0, v14, v14
	v_fmac_f32_e32 v13, v16, v16
	v_add_f32_e32 v0, v0, v13
	s_waitcnt vmcnt(12)
	v_mov_b32_e32 v18, v186
	v_mov_b32_e32 v19, v187
	v_mov_b32_e32 v20, v188
	v_mov_b32_e32 v21, v189
	v_mov_b32_e32 v22, v190
	v_mov_b32_e32 v23, v191
	v_mov_b32_e32 v24, v192
	v_mov_b32_e32 v25, v193
	v_mov_b32_e32 v26, v194
	v_mov_b32_e32 v27, v195
	v_mov_b32_e32 v28, v196
	v_mov_b32_e32 v29, v197
	v_mov_b32_e32 v30, v198
	v_mov_b32_e32 v31, v199
	v_mov_b32_e32 v32, v200
	v_mov_b32_e32 v33, v201
	v_mov_b32_e32 v34, v202
	v_mov_b32_e32 v35, v203
	v_mov_b32_e32 v36, v204
	v_mov_b32_e32 v37, v205
	v_pk_add_f32 v[20:21], v[20:21], v[24:25]
	v_pk_add_f32 v[18:19], v[18:19], v[22:23]
	v_pk_add_f32 v[20:21], v[20:21], v[28:29]
	v_pk_add_f32 v[18:19], v[18:19], v[26:27]
	v_pk_add_f32 v[20:21], v[20:21], v[32:33]
	v_pk_add_f32 v[18:19], v[18:19], v[30:31]
	v_pk_add_f32 v[20:21], v[20:21], v[36:37]
	v_pk_add_f32 v[18:19], v[18:19], v[34:35]
	global_store_dwordx4 v[40:41], v[18:21], off
	v_cvt_pk_bf16_f32 v22, v18, v19
	v_cvt_pk_bf16_f32 v23, v20, v21
	global_store_dwordx2 v[38:39], v[22:23], off
	s_nop 0
	v_mul_f32_e32 v13, v19, v19
	v_mul_f32_e32 v14, v21, v21
	v_fmac_f32_e32 v13, v18, v18
	v_fmac_f32_e32 v14, v20, v20
	v_add_f32_e32 v13, v13, v14
	v_add_f32_e32 v0, v0, v13
	s_waitcnt vmcnt(9)
	v_mov_b32_e32 v22, v206
	v_mov_b32_e32 v23, v207
	v_mov_b32_e32 v24, v208
	v_mov_b32_e32 v25, v209
	v_mov_b32_e32 v26, v210
	v_mov_b32_e32 v27, v211
	v_mov_b32_e32 v28, v212
	v_mov_b32_e32 v29, v213
	v_mov_b32_e32 v30, v214
	v_mov_b32_e32 v31, v215
	v_mov_b32_e32 v32, v216
	v_mov_b32_e32 v33, v217
	v_mov_b32_e32 v34, v218
	v_mov_b32_e32 v35, v219
	v_mov_b32_e32 v36, v220
	v_mov_b32_e32 v37, v221
	v_mov_b32_e32 v38, v222
	v_mov_b32_e32 v39, v223
	v_mov_b32_e32 v40, v224
	v_mov_b32_e32 v41, v225
	v_pk_add_f32 v[24:25], v[24:25], v[28:29]
	v_pk_add_f32 v[22:23], v[22:23], v[26:27]
	v_pk_add_f32 v[24:25], v[24:25], v[32:33]
	v_pk_add_f32 v[22:23], v[22:23], v[30:31]
	v_pk_add_f32 v[24:25], v[24:25], v[36:37]
	v_pk_add_f32 v[22:23], v[22:23], v[34:35]
	v_pk_add_f32 v[24:25], v[24:25], v[40:41]
	v_pk_add_f32 v[22:23], v[22:23], v[38:39]
	global_store_dwordx4 v[44:45], v[22:25], off
	v_cvt_pk_bf16_f32 v26, v22, v23
	v_cvt_pk_bf16_f32 v27, v24, v25
	global_store_dwordx2 v[42:43], v[26:27], off
	s_nop 0
	v_mul_f32_e32 v13, v23, v23
	v_mul_f32_e32 v14, v25, v25
	v_fmac_f32_e32 v13, v22, v22
	v_fmac_f32_e32 v14, v24, v24
	v_add_f32_e32 v13, v13, v14
	v_add_f32_e32 v0, v0, v13
	s_waitcnt vmcnt(6)
	v_mov_b32_e32 v26, v226
	v_mov_b32_e32 v27, v227
	v_mov_b32_e32 v28, v228
	v_mov_b32_e32 v29, v229
	v_mov_b32_e32 v30, v232
	v_mov_b32_e32 v31, v233
	v_mov_b32_e32 v32, v234
	v_mov_b32_e32 v33, v235
	v_mov_b32_e32 v34, v236
	v_mov_b32_e32 v35, v237
	v_mov_b32_e32 v36, v238
	v_mov_b32_e32 v37, v239
	v_mov_b32_e32 v38, v240
	v_mov_b32_e32 v39, v241
	v_mov_b32_e32 v40, v242
	v_mov_b32_e32 v41, v243
	v_mov_b32_e32 v42, v244
	v_mov_b32_e32 v43, v245
	v_mov_b32_e32 v44, v246
	v_mov_b32_e32 v45, v247
	v_pk_add_f32 v[14:15], v[28:29], v[32:33]
	v_pk_add_f32 v[16:17], v[26:27], v[30:31]
	v_pk_add_f32 v[14:15], v[14:15], v[36:37]
	v_pk_add_f32 v[16:17], v[16:17], v[34:35]
	v_pk_add_f32 v[14:15], v[14:15], v[40:41]
	v_pk_add_f32 v[18:19], v[16:17], v[38:39]
	v_pk_add_f32 v[16:17], v[14:15], v[44:45]
	v_pk_add_f32 v[14:15], v[18:19], v[42:43]
	v_mul_f32_e32 v18, v17, v17
	v_mul_f32_e32 v13, v15, v15
	v_fmac_f32_e32 v13, v14, v14
	v_fmac_f32_e32 v18, v16, v16
	v_add_f32_e32 v13, v13, v18
	v_add_f32_e32 v0, v0, v13
	ds_bpermute_b32 v1, v1, v0
	global_store_dwordx4 v[54:55], v[14:17], off
	s_waitcnt lgkmcnt(0)
	v_add_f32_e32 v0, v0, v1
	ds_bpermute_b32 v1, v8, v0
	v_cvt_pk_bf16_f32 v8, v14, v15
	s_waitcnt lgkmcnt(0)
	v_add_f32_e32 v0, v0, v1
	ds_bpermute_b32 v1, v9, v0
	v_cvt_pk_bf16_f32 v9, v16, v17
	global_store_dwordx2 v[4:5], v[8:9], off
	s_waitcnt lgkmcnt(0)
	v_add_f32_e32 v0, v0, v1
	ds_bpermute_b32 v1, v10, v0
	s_waitcnt lgkmcnt(0)
	v_add_f32_e32 v0, v0, v1
	ds_bpermute_b32 v1, v11, v0
	s_waitcnt lgkmcnt(0)
	v_add_f32_e32 v0, v0, v1
	ds_bpermute_b32 v1, v12, v0
	s_and_saveexec_b64 s[12:13], s[10:11]
	s_cbranch_execz .LBB0_1158
	v_lshlrev_b64 v[2:3], 6, v[2:3]
	s_waitcnt lgkmcnt(0)
	v_add_f32_e32 v0, v0, v1
	v_lshl_add_u64 v[2:3], v[6:7], 0, v[2:3]
	v_cndmask_b32_e32 v0, 0, v0, vcc
	global_store_dword v[2:3], v0, off

; __device__ __forceinline__ unsigned pk2(float lo, float hi) { unsigned r; asm volatile("v_cvt_pk_bf16_f32 %0, %1, %2" : "=v"(r) : "v"(lo), "v"(hi)); return r; }
;     ...
;         const int lane = threadIdx.x & 63, wv = threadIdx.x >> 6;
;         const int rbase = u.pm * 256 + (kq * 4 + u.pn) * 16 + wv * 2;
; #pragma unroll
;         for (int rr = 0; rr < 2; ++rr) {
;             const int row = rbase + rr; float sq = 0.f;
; #pragma unroll
;             for (int i = 0; i < 4; ++i) {
;                 const size_t o = (size_t)row * DM + i * 256 + lane * 4;
;                 f32x4 v = *(const f32x4*)(xold + o);
; #pragma unroll
;                 for (int q = 0; q < 4; ++q) v += *(const f32x4*)(part + (size_t)q * 1024 * DM + o);
;                 *(f32x4*)(xf_s + o) = v;
;                 u32x2 w; w.x = pk2(v[0], v[1]); w.y = pk2(v[2], v[3]); *(u32x2*)(xb_s + o) = w;
;                 sq += (v[0] * v[0] + v[1] * v[1]) + (v[2] * v[2] + v[3] * v[3]);
.LBB0_2020:
	s_or_b64 exec, exec, s[8:9]
	s_add_u32 s18, s24, 0x4000000
	s_addc_u32 s19, s25, 0
	s_add_u32 s16, s16, 0x2000000
	s_addc_u32 s17, s17, 0
	s_lshr_b32 s8, s71, 2
	v_lshrrev_b32_e32 v0, 5, v166
	s_and_b32 s8, s8, 0xffffffc
	v_and_b32_e32 v0, 30, v0
	s_add_i32 s6, s6, s8
	v_lshl_or_b32 v0, s7, 8, v0
	v_lshl_add_u32 v2, s6, 4, v0
	v_ashrrev_i32_e32 v3, 31, v2
	v_lshlrev_b32_e32 v0, 2, v167
	v_lshlrev_b64 v[4:5], 10, v[2:3]
	v_or_b32_e32 v4, v4, v0
	v_lshlrev_b64 v[10:11], 2, v[4:5]
	v_lshl_add_u64 v[38:39], s[12:13], 0, v[10:11]
	s_mov_b32 s6, 0x400000
	v_add_co_u32_e32 v40, vcc, s6, v38
	s_mov_b32 s7, 0x800000
	s_nop 0
	v_addc_co_u32_e32 v41, vcc, 0, v39, vcc
	v_lshl_add_u64 v[26:27], s[18:19], 0, v[10:11]
	v_add_co_u32_e32 v42, vcc, s7, v38
	s_barrier
	global_load_dwordx4 v[6:9], v[26:27], off
	v_addc_co_u32_e32 v43, vcc, 0, v39, vcc
	s_mov_b32 s22, 0xc00000
	global_load_dwordx4 v[10:13], v[38:39], off
	global_load_dwordx4 v[14:17], v[40:41], off
	v_add_co_u32_e32 v44, vcc, s22, v38
	global_load_dwordx4 v[18:21], v[42:43], off
	s_nop 0
	v_addc_co_u32_e32 v45, vcc, 0, v39, vcc
	global_load_dwordx4 v[22:25], v[44:45], off
	v_mov_b32_e32 v31, v5
	v_lshl_add_u64 v[28:29], v[4:5], 1, s[16:17]
	v_or_b32_e32 v30, 0x100, v4
	v_lshl_add_u64 v[32:33], v[30:31], 2, s[18:19]
	v_mov_b32_e32 v35, v5
	v_or_b32_e32 v34, 0x200, v4
	v_lshl_add_u64 v[30:31], v[30:31], 1, s[16:17]
	v_lshl_add_u64 v[36:37], v[34:35], 2, s[18:19]
	v_or_b32_e32 v4, 0x300, v4
	v_lshl_add_u64 v[34:35], v[34:35], 1, s[16:17]
	v_lshl_add_u64 v[46:47], v[4:5], 2, s[18:19]
	v_mov_b32_e32 v1, 0
	s_mov_b64 s[20:21], 0x100000
	v_cmp_gt_u32_e64 s[8:9], 16, v167
	v_cmp_eq_u32_e32 vcc, 0, v167
	v_lshl_add_u64 v[4:5], v[4:5], 1, s[16:17]
	global_load_dwordx4 v[186:189], v[32:33], off
	global_load_dwordx4 v[190:193], v[38:39], off offset:1024
	global_load_dwordx4 v[194:197], v[40:41], off offset:1024
	global_load_dwordx4 v[198:201], v[42:43], off offset:1024
	global_load_dwordx4 v[202:205], v[44:45], off offset:1024
	global_load_dwordx4 v[206:209], v[36:37], off
	global_load_dwordx4 v[210:213], v[38:39], off offset:2048
	global_load_dwordx4 v[214:217], v[40:41], off offset:2048
	global_load_dwordx4 v[218:221], v[42:43], off offset:2048
	global_load_dwordx4 v[222:225], v[44:45], off offset:2048
	global_load_dwordx4 v[226:229], v[46:47], off
	global_load_dwordx4 v[232:235], v[38:39], off offset:3072
	global_load_dwordx4 v[236:239], v[40:41], off offset:3072
	global_load_dwordx4 v[240:243], v[42:43], off offset:3072
	global_load_dwordx4 v[244:247], v[44:45], off offset:3072
	s_waitcnt vmcnt(18)
	v_pk_add_f32 v[8:9], v[8:9], v[12:13]
	v_pk_add_f32 v[6:7], v[6:7], v[10:11]
	s_waitcnt vmcnt(17)
	v_pk_add_f32 v[8:9], v[8:9], v[16:17]
	v_pk_add_f32 v[6:7], v[6:7], v[14:15]
	s_waitcnt vmcnt(16)
	v_pk_add_f32 v[8:9], v[8:9], v[20:21]
	v_pk_add_f32 v[6:7], v[6:7], v[18:19]
	s_waitcnt vmcnt(15)
	v_pk_add_f32 v[8:9], v[8:9], v[24:25]
	v_pk_add_f32 v[6:7], v[6:7], v[22:23]
	global_store_dwordx4 v[26:27], v[6:9], off
	v_cvt_pk_bf16_f32 v10, v6, v7
	v_cvt_pk_bf16_f32 v11, v8, v9
	global_store_dwordx2 v[28:29], v[10:11], off
	s_nop 0
	v_mul_f32_e32 v7, v7, v7
	v_mul_f32_e32 v9, v9, v9
	v_fmac_f32_e32 v7, v6, v6
	v_fmac_f32_e32 v9, v8, v8
	v_add_f32_e32 v6, v7, v9
	s_waitcnt vmcnt(12)
	v_mov_b32_e32 v10, v186
	v_mov_b32_e32 v11, v187
	v_mov_b32_e32 v12, v188
	v_mov_b32_e32 v13, v189
	v_mov_b32_e32 v14, v190
	v_mov_b32_e32 v15, v191
	v_mov_b32_e32 v16, v192
	v_mov_b32_e32 v17, v193
	v_mov_b32_e32 v18, v194
	v_mov_b32_e32 v19, v195
	v_mov_b32_e32 v20, v196
	v_mov_b32_e32 v21, v197
	v_mov_b32_e32 v22, v198
	v_mov_b32_e32 v23, v199
	v_mov_b32_e32 v24, v200
	v_mov_b32_e32 v25, v201
	v_mov_b32_e32 v26, v202
	v_mov_b32_e32 v27, v203
	v_mov_b32_e32 v28, v204
	v_mov_b32_e32 v29, v205
	v_pk_add_f32 v[12:13], v[12:13], v[16:17]
	v_pk_add_f32 v[10:11], v[10:11], v[14:15]
	v_pk_add_f32 v[12:13], v[12:13], v[20:21]
	v_pk_add_f32 v[10:11], v[10:11], v[18:19]
	v_pk_add_f32 v[12:13], v[12:13], v[24:25]
	v_pk_add_f32 v[10:11], v[10:11], v[22:23]
	v_pk_add_f32 v[12:13], v[12:13], v[28:29]
	v_pk_add_f32 v[10:11], v[10:11], v[26:27]
	global_store_dwordx4 v[32:33], v[10:13], off
	v_cvt_pk_bf16_f32 v14, v10, v11
	v_cvt_pk_bf16_f32 v15, v12, v13
	global_store_dwordx2 v[30:31], v[14:15], off
	s_nop 0
	v_mul_f32_e32 v7, v11, v11
	v_mul_f32_e32 v8, v13, v13
	v_fmac_f32_e32 v7, v10, v10
	v_fmac_f32_e32 v8, v12, v12
	v_add_f32_e32 v7, v7, v8
	v_add_f32_e32 v6, v6, v7
	s_waitcnt vmcnt(9)
	v_mov_b32_e32 v14, v206
	v_mov_b32_e32 v15, v207
	v_mov_b32_e32 v16, v208
	v_mov_b32_e32 v17, v209
	v_mov_b32_e32 v18, v210
	v_mov_b32_e32 v19, v211
	v_mov_b32_e32 v20, v212
	v_mov_b32_e32 v21, v213
	v_mov_b32_e32 v22, v214
	v_mov_b32_e32 v23, v215
	v_mov_b32_e32 v24, v216
	v_mov_b32_e32 v25, v217
	v_mov_b32_e32 v26, v218
	v_mov_b32_e32 v27, v219
	v_mov_b32_e32 v28, v220
	v_mov_b32_e32 v29, v221
	v_mov_b32_e32 v30, v222
	v_mov_b32_e32 v31, v223
	v_mov_b32_e32 v32, v224
	v_mov_b32_e32 v33, v225
	v_pk_add_f32 v[16:17], v[16:17], v[20:21]
	v_pk_add_f32 v[14:15], v[14:15], v[18:19]
	v_pk_add_f32 v[16:17], v[16:17], v[24:25]
	v_pk_add_f32 v[14:15], v[14:15], v[22:23]
	v_pk_add_f32 v[16:17], v[16:17], v[28:29]
	v_pk_add_f32 v[14:15], v[14:15], v[26:27]
	v_pk_add_f32 v[16:17], v[16:17], v[32:33]
	v_pk_add_f32 v[14:15], v[14:15], v[30:31]
	global_store_dwordx4 v[36:37], v[14:17], off
	v_cvt_pk_bf16_f32 v18, v14, v15
	v_cvt_pk_bf16_f32 v19, v16, v17
	global_store_dwordx2 v[34:35], v[18:19], off
	s_nop 0
	v_mul_f32_e32 v7, v15, v15
	v_mul_f32_e32 v8, v17, v17
	v_fmac_f32_e32 v7, v14, v14
	v_fmac_f32_e32 v8, v16, v16
	v_add_f32_e32 v7, v7, v8
	v_add_f32_e32 v10, v6, v7
	v_mbcnt_hi_u32_b32 v40, -1, v168
	v_lshl_add_u64 v[38:39], s[14:15], 0, v[0:1]
	v_and_b32_e32 v1, 64, v40
	v_xor_b32_e32 v41, 32, v40
	v_add_u32_e32 v43, 64, v1
	v_cmp_lt_i32_e64 s[10:11], v41, v43
	v_xor_b32_e32 v42, 16, v40
	v_xor_b32_e32 v11, 2, v40
	v_cndmask_b32_e64 v1, v40, v41, s[10:11]
	v_lshlrev_b32_e32 v1, 2, v1
	v_cmp_lt_i32_e64 s[10:11], v42, v43
	v_xor_b32_e32 v12, 1, v40
	s_waitcnt vmcnt(6)
; __device__ __forceinline__ unsigned pk2(float lo, float hi) { unsigned r; asm volatile("v_cvt_pk_bf16_f32 %0, %1, %2" : "=v"(r) : "v"(lo), "v"(hi)); return r; }
;     ...
;         for (int rr = 0; rr < 2; ++rr) {
;             const int row = rbase + rr; float sq = 0.f;
; #pragma unroll
;             for (int i = 0; i < 4; ++i) {
;                 const size_t o = (size_t)row * DM + i * 256 + lane * 4;
;                 f32x4 v = *(const f32x4*)(xold + o);
; #pragma unroll
;                 for (int q = 0; q < 4; ++q) v += *(const f32x4*)(part + (size_t)q * 1024 * DM + o);
;                 *(f32x4*)(xf_s + o) = v;
;                 u32x2 w; w.x = pk2(v[0], v[1]); w.y = pk2(v[2], v[3]); *(u32x2*)(xb_s + o) = w;
;                 sq += (v[0] * v[0] + v[1] * v[1]) + (v[2] * v[2] + v[3] * v[3]);
;             }
; #pragma unroll
;             for (int o = 32; o >= 1; o >>= 1) sq += __shfl_xor(sq, o);
;             if (lane < 16) ssq_s[(size_t)row * 16 + lane] = lane == 0 ? sq : 0.f;
;         }
	v_mov_b32_e32 v18, v226
	v_mov_b32_e32 v19, v227
	v_mov_b32_e32 v20, v228
	v_mov_b32_e32 v21, v229
	v_mov_b32_e32 v22, v232
	v_mov_b32_e32 v23, v233
	v_mov_b32_e32 v24, v234
	v_mov_b32_e32 v25, v235
	v_mov_b32_e32 v26, v236
	v_mov_b32_e32 v27, v237
	v_mov_b32_e32 v28, v238
	v_mov_b32_e32 v29, v239
	v_mov_b32_e32 v30, v240
	v_mov_b32_e32 v31, v241
	v_mov_b32_e32 v32, v242
	v_mov_b32_e32 v33, v243
	v_mov_b32_e32 v34, v244
	v_mov_b32_e32 v35, v245
	v_mov_b32_e32 v36, v246
	v_mov_b32_e32 v37, v247
	v_pk_add_f32 v[6:7], v[20:21], v[24:25]
	v_pk_add_f32 v[8:9], v[18:19], v[22:23]
	v_pk_add_f32 v[6:7], v[6:7], v[28:29]
	v_pk_add_f32 v[8:9], v[8:9], v[26:27]
	v_pk_add_f32 v[6:7], v[6:7], v[32:33]
	v_pk_add_f32 v[8:9], v[8:9], v[30:31]
	v_pk_add_f32 v[18:19], v[6:7], v[36:37]
	v_pk_add_f32 v[16:17], v[8:9], v[34:35]
	v_mul_f32_e32 v7, v19, v19
	v_mul_f32_e32 v6, v17, v17
	v_fmac_f32_e32 v6, v16, v16
	v_fmac_f32_e32 v7, v18, v18
	v_add_f32_e32 v6, v6, v7
	v_add_f32_e32 v6, v10, v6
	ds_bpermute_b32 v7, v1, v6
	v_cndmask_b32_e64 v8, v40, v42, s[10:11]
	v_lshlrev_b32_e32 v8, 2, v8
	v_xor_b32_e32 v9, 8, v40
	v_cmp_lt_i32_e64 s[10:11], v9, v43
	s_waitcnt lgkmcnt(0)
	v_add_f32_e32 v6, v6, v7
	ds_bpermute_b32 v7, v8, v6
	v_cndmask_b32_e64 v9, v40, v9, s[10:11]
	v_lshlrev_b32_e32 v9, 2, v9
	v_xor_b32_e32 v10, 4, v40
	v_cmp_lt_i32_e64 s[10:11], v10, v43
	s_waitcnt lgkmcnt(0)
	v_add_f32_e32 v6, v6, v7
	ds_bpermute_b32 v7, v9, v6
	v_cndmask_b32_e64 v10, v40, v10, s[10:11]
	v_lshlrev_b32_e32 v10, 2, v10
	v_cmp_lt_i32_e64 s[10:11], v11, v43
	global_store_dwordx4 v[46:47], v[16:19], off
	s_waitcnt lgkmcnt(0)
	v_add_f32_e32 v6, v6, v7
	ds_bpermute_b32 v7, v10, v6
	v_cndmask_b32_e64 v11, v40, v11, s[10:11]
	v_lshlrev_b32_e32 v11, 2, v11
	v_cmp_lt_i32_e64 s[10:11], v12, v43
	v_cvt_pk_bf16_f32 v16, v16, v17
	s_waitcnt lgkmcnt(0)
	v_add_f32_e32 v13, v6, v7
	ds_bpermute_b32 v14, v11, v13
	v_cndmask_b32_e64 v12, v40, v12, s[10:11]
	v_lshlrev_b32_e32 v12, 2, v12
	v_lshl_add_u64 v[6:7], v[38:39], 0, s[20:21]
	v_cvt_pk_bf16_f32 v17, v18, v19
	s_waitcnt lgkmcnt(0)
	v_add_f32_e32 v13, v13, v14
	ds_bpermute_b32 v14, v12, v13
	global_store_dwordx2 v[4:5], v[16:17], off
	s_and_saveexec_b64 s[10:11], s[8:9]
	s_cbranch_execz .LBB0_2022
	v_lshlrev_b64 v[4:5], 6, v[2:3]
	s_waitcnt lgkmcnt(0)
	v_add_f32_e32 v3, v13, v14
	v_lshl_add_u64 v[4:5], v[6:7], 0, v[4:5]
	v_cndmask_b32_e32 v3, 0, v3, vcc
	global_store_dword v[4:5], v3, off
.LBB0_2022:
	s_or_b64 exec, exec, s[10:11]
	v_or_b32_e32 v2, 1, v2
	v_ashrrev_i32_e32 v3, 31, v2
	v_lshlrev_b64 v[4:5], 10, v[2:3]
	v_or_b32_e32 v4, v4, v0
	v_lshlrev_b64 v[18:19], 2, v[4:5]
	v_lshl_add_u64 v[46:47], s[12:13], 0, v[18:19]
	v_add_co_u32_e64 v48, s[10:11], s6, v46
	v_lshl_add_u64 v[34:35], s[18:19], 0, v[18:19]
	s_nop 0
	v_addc_co_u32_e64 v49, s[10:11], 0, v47, s[10:11]
	v_add_co_u32_e64 v50, s[10:11], s7, v46
	s_waitcnt lgkmcnt(0)
	global_load_dwordx4 v[14:17], v[34:35], off
	v_addc_co_u32_e64 v51, s[10:11], 0, v47, s[10:11]
	global_load_dwordx4 v[18:21], v[46:47], off
	global_load_dwordx4 v[22:25], v[48:49], off
	v_add_co_u32_e64 v52, s[10:11], s22, v46
	global_load_dwordx4 v[26:29], v[50:51], off
	s_nop 0
	v_addc_co_u32_e64 v53, s[10:11], 0, v47, s[10:11]
	global_load_dwordx4 v[30:33], v[52:53], off
	v_mov_b32_e32 v39, v5
	v_lshl_add_u64 v[36:37], v[4:5], 1, s[16:17]
	v_or_b32_e32 v38, 0x100, v4
	v_lshl_add_u64 v[40:41], v[38:39], 2, s[18:19]
	v_mov_b32_e32 v43, v5
	v_or_b32_e32 v42, 0x200, v4
	v_lshl_add_u64 v[38:39], v[38:39], 1, s[16:17]
	v_lshl_add_u64 v[44:45], v[42:43], 2, s[18:19]
	v_or_b32_e32 v4, 0x300, v4
	v_lshl_add_u64 v[42:43], v[42:43], 1, s[16:17]
	v_lshl_add_u64 v[54:55], v[4:5], 2, s[18:19]
	v_lshl_add_u64 v[4:5], v[4:5], 1, s[16:17]
	global_load_dwordx4 v[186:189], v[40:41], off
	global_load_dwordx4 v[190:193], v[46:47], off offset:1024
	global_load_dwordx4 v[194:197], v[48:49], off offset:1024
	global_load_dwordx4 v[198:201], v[50:51], off offset:1024
	global_load_dwordx4 v[202:205], v[52:53], off offset:1024
	global_load_dwordx4 v[206:209], v[44:45], off
	global_load_dwordx4 v[210:213], v[46:47], off offset:2048
	global_load_dwordx4 v[214:217], v[48:49], off offset:2048
	global_load_dwordx4 v[218:221], v[50:51], off offset:2048
	global_load_dwordx4 v[222:225], v[52:53], off offset:2048
	global_load_dwordx4 v[226:229], v[54:55], off
	global_load_dwordx4 v[232:235], v[46:47], off offset:3072
	global_load_dwordx4 v[236:239], v[48:49], off offset:3072
	global_load_dwordx4 v[240:243], v[50:51], off offset:3072
	global_load_dwordx4 v[244:247], v[52:53], off offset:3072
	s_waitcnt vmcnt(18)
	v_pk_add_f32 v[16:17], v[16:17], v[20:21]
	v_pk_add_f32 v[14:15], v[14:15], v[18:19]
	s_waitcnt vmcnt(17)
	v_pk_add_f32 v[16:17], v[16:17], v[24:25]
	v_pk_add_f32 v[14:15], v[14:15], v[22:23]
	s_waitcnt vmcnt(16)
; __device__ __forceinline__ unsigned pk2(float lo, float hi) { unsigned r; asm volatile("v_cvt_pk_bf16_f32 %0, %1, %2" : "=v"(r) : "v"(lo), "v"(hi)); return r; }
;     ...
;             for (int i = 0; i < 4; ++i) {
;                 const size_t o = (size_t)row * DM + i * 256 + lane * 4;
;                 f32x4 v = *(const f32x4*)(xold + o);
; #pragma unroll
;                 for (int q = 0; q < 4; ++q) v += *(const f32x4*)(part + (size_t)q * 1024 * DM + o);
;                 *(f32x4*)(xf_s + o) = v;
;                 u32x2 w; w.x = pk2(v[0], v[1]); w.y = pk2(v[2], v[3]); *(u32x2*)(xb_s + o) = w;
;                 sq += (v[0] * v[0] + v[1] * v[1]) + (v[2] * v[2] + v[3] * v[3]);
;             }
; #pragma unroll
;             for (int o = 32; o >= 1; o >>= 1) sq += __shfl_xor(sq, o);
;             if (lane < 16) ssq_s[(size_t)row * 16 + lane] = lane == 0 ? sq : 0.f;
;         }
	v_pk_add_f32 v[16:17], v[16:17], v[28:29]
	v_pk_add_f32 v[14:15], v[14:15], v[26:27]
	s_waitcnt vmcnt(15)
	v_pk_add_f32 v[16:17], v[16:17], v[32:33]
	v_pk_add_f32 v[14:15], v[14:15], v[30:31]
	global_store_dwordx4 v[34:35], v[14:17], off
	v_cvt_pk_bf16_f32 v18, v14, v15
	v_cvt_pk_bf16_f32 v19, v16, v17
	global_store_dwordx2 v[36:37], v[18:19], off
	s_nop 0
	v_mul_f32_e32 v0, v15, v15
	v_mul_f32_e32 v13, v17, v17
	v_fmac_f32_e32 v0, v14, v14
	v_fmac_f32_e32 v13, v16, v16
	v_add_f32_e32 v0, v0, v13
	s_waitcnt vmcnt(12)
	v_mov_b32_e32 v18, v186
	v_mov_b32_e32 v19, v187
	v_mov_b32_e32 v20, v188
	v_mov_b32_e32 v21, v189
	v_mov_b32_e32 v22, v190
	v_mov_b32_e32 v23, v191
	v_mov_b32_e32 v24, v192
	v_mov_b32_e32 v25, v193
	v_mov_b32_e32 v26, v194
	v_mov_b32_e32 v27, v195
	v_mov_b32_e32 v28, v196
	v_mov_b32_e32 v29, v197
	v_mov_b32_e32 v30, v198
	v_mov_b32_e32 v31, v199
	v_mov_b32_e32 v32, v200
	v_mov_b32_e32 v33, v201
	v_mov_b32_e32 v34, v202
	v_mov_b32_e32 v35, v203
	v_mov_b32_e32 v36, v204
	v_mov_b32_e32 v37, v205
	v_pk_add_f32 v[20:21], v[20:21], v[24:25]
	v_pk_add_f32 v[18:19], v[18:19], v[22:23]
	v_pk_add_f32 v[20:21], v[20:21], v[28:29]
	v_pk_add_f32 v[18:19], v[18:19], v[26:27]
	v_pk_add_f32 v[20:21], v[20:21], v[32:33]
	v_pk_add_f32 v[18:19], v[18:19], v[30:31]
	v_pk_add_f32 v[20:21], v[20:21], v[36:37]
	v_pk_add_f32 v[18:19], v[18:19], v[34:35]
	global_store_dwordx4 v[40:41], v[18:21], off
	v_cvt_pk_bf16_f32 v22, v18, v19
	v_cvt_pk_bf16_f32 v23, v20, v21
	global_store_dwordx2 v[38:39], v[22:23], off
	s_nop 0
	v_mul_f32_e32 v13, v19, v19
	v_mul_f32_e32 v14, v21, v21
	v_fmac_f32_e32 v13, v18, v18
	v_fmac_f32_e32 v14, v20, v20
	v_add_f32_e32 v13, v13, v14
	v_add_f32_e32 v0, v0, v13
	s_waitcnt vmcnt(9)
	v_mov_b32_e32 v22, v206
	v_mov_b32_e32 v23, v207
	v_mov_b32_e32 v24, v208
	v_mov_b32_e32 v25, v209
	v_mov_b32_e32 v26, v210
	v_mov_b32_e32 v27, v211
	v_mov_b32_e32 v28, v212
	v_mov_b32_e32 v29, v213
	v_mov_b32_e32 v30, v214
	v_mov_b32_e32 v31, v215
	v_mov_b32_e32 v32, v216
	v_mov_b32_e32 v33, v217
	v_mov_b32_e32 v34, v218
	v_mov_b32_e32 v35, v219
	v_mov_b32_e32 v36, v220
	v_mov_b32_e32 v37, v221
	v_mov_b32_e32 v38, v222
	v_mov_b32_e32 v39, v223
	v_mov_b32_e32 v40, v224
	v_mov_b32_e32 v41, v225
	v_pk_add_f32 v[24:25], v[24:25], v[28:29]
	v_pk_add_f32 v[22:23], v[22:23], v[26:27]
	v_pk_add_f32 v[24:25], v[24:25], v[32:33]
	v_pk_add_f32 v[22:23], v[22:23], v[30:31]
	v_pk_add_f32 v[24:25], v[24:25], v[36:37]
	v_pk_add_f32 v[22:23], v[22:23], v[34:35]
	v_pk_add_f32 v[24:25], v[24:25], v[40:41]
	v_pk_add_f32 v[22:23], v[22:23], v[38:39]
	global_store_dwordx4 v[44:45], v[22:25], off
	v_cvt_pk_bf16_f32 v26, v22, v23
	v_cvt_pk_bf16_f32 v27, v24, v25
	global_store_dwordx2 v[42:43], v[26:27], off
	s_nop 0
	v_mul_f32_e32 v13, v23, v23
	v_mul_f32_e32 v14, v25, v25
	v_fmac_f32_e32 v13, v22, v22
	v_fmac_f32_e32 v14, v24, v24
	v_add_f32_e32 v13, v13, v14
	v_add_f32_e32 v0, v0, v13
	s_waitcnt vmcnt(6)
	v_mov_b32_e32 v26, v226
	v_mov_b32_e32 v27, v227
	v_mov_b32_e32 v28, v228
	v_mov_b32_e32 v29, v229
	v_mov_b32_e32 v30, v232
	v_mov_b32_e32 v31, v233
	v_mov_b32_e32 v32, v234
	v_mov_b32_e32 v33, v235
	v_mov_b32_e32 v34, v236
	v_mov_b32_e32 v35, v237
	v_mov_b32_e32 v36, v238
	v_mov_b32_e32 v37, v239
	v_mov_b32_e32 v38, v240
	v_mov_b32_e32 v39, v241
	v_mov_b32_e32 v40, v242
	v_mov_b32_e32 v41, v243
	v_mov_b32_e32 v42, v244
	v_mov_b32_e32 v43, v245
	v_mov_b32_e32 v44, v246
	v_mov_b32_e32 v45, v247
	v_pk_add_f32 v[14:15], v[28:29], v[32:33]
	v_pk_add_f32 v[16:17], v[26:27], v[30:31]
	v_pk_add_f32 v[14:15], v[14:15], v[36:37]
	v_pk_add_f32 v[16:17], v[16:17], v[34:35]
	v_pk_add_f32 v[14:15], v[14:15], v[40:41]
	v_pk_add_f32 v[18:19], v[16:17], v[38:39]
	v_pk_add_f32 v[16:17], v[14:15], v[44:45]
	v_pk_add_f32 v[14:15], v[18:19], v[42:43]
	v_mul_f32_e32 v18, v17, v17
	v_mul_f32_e32 v13, v15, v15
	v_fmac_f32_e32 v13, v14, v14
	v_fmac_f32_e32 v18, v16, v16
	v_add_f32_e32 v13, v13, v18
	v_add_f32_e32 v0, v0, v13
	ds_bpermute_b32 v1, v1, v0
	global_store_dwordx4 v[54:55], v[14:17], off
	s_waitcnt lgkmcnt(0)
	v_add_f32_e32 v0, v0, v1
	ds_bpermute_b32 v1, v8, v0
	v_cvt_pk_bf16_f32 v8, v14, v15
	s_waitcnt lgkmcnt(0)
	v_add_f32_e32 v0, v0, v1
	ds_bpermute_b32 v1, v9, v0
	v_cvt_pk_bf16_f32 v9, v16, v17
	global_store_dwordx2 v[4:5], v[8:9], off
	s_waitcnt lgkmcnt(0)
	v_add_f32_e32 v0, v0, v1
	ds_bpermute_b32 v1, v10, v0
	s_waitcnt lgkmcnt(0)
	v_add_f32_e32 v0, v0, v1
	ds_bpermute_b32 v1, v11, v0
	s_waitcnt lgkmcnt(0)
	v_add_f32_e32 v0, v0, v1
	ds_bpermute_b32 v1, v12, v0
	s_and_saveexec_b64 s[10:11], s[8:9]
	s_cbranch_execz .LBB0_2024
	v_lshlrev_b64 v[2:3], 6, v[2:3]
	s_waitcnt lgkmcnt(0)
	v_add_f32_e32 v0, v0, v1
	v_lshl_add_u64 v[2:3], v[6:7], 0, v[2:3]
	v_cndmask_b32_e32 v0, 0, v0, vcc
	global_store_dword v[2:3], v0, off

; __device__ __forceinline__ unsigned pk2(float lo, float hi) { unsigned r; asm volatile("v_cvt_pk_bf16_f32 %0, %1, %2" : "=v"(r) : "v"(lo), "v"(hi)); return r; }
;     ...
;         const int lane = threadIdx.x & 63, wv = threadIdx.x >> 6;
;         const int rbase = u.pm * 256 + (kq * 4 + u.pn) * 16 + wv * 2;
; #pragma unroll
;         for (int rr = 0; rr < 2; ++rr) {
;             const int row = rbase + rr; float sq = 0.f;
; #pragma unroll
;             for (int i = 0; i < 4; ++i) {
;                 const size_t o = (size_t)row * DM + i * 256 + lane * 4;
;                 f32x4 v = *(const f32x4*)(xold + o);
; #pragma unroll
;                 for (int q = 0; q < 4; ++q) v += *(const f32x4*)(part + (size_t)q * 1024 * DM + o);
;                 *(f32x4*)(xf_s + o) = v;
;                 u32x2 w; w.x = pk2(v[0], v[1]); w.y = pk2(v[2], v[3]); *(u32x2*)(xb_s + o) = w;
;                 sq += (v[0] * v[0] + v[1] * v[1]) + (v[2] * v[2] + v[3] * v[3]);
.LBB0_2262:
	s_or_b64 exec, exec, s[6:7]
	s_add_u32 s14, s16, 0x4000000
	s_addc_u32 s15, s17, 0
	s_add_u32 s12, s12, 0x2000000
	s_addc_u32 s13, s13, 0
	s_lshr_b32 s6, s51, 2
	v_lshrrev_b32_e32 v0, 5, v166
	s_and_b32 s6, s6, 0xffffffc
	v_and_b32_e32 v0, 30, v0
	s_add_i32 s22, s22, s6
	v_lshl_or_b32 v0, s23, 8, v0
	v_lshl_add_u32 v2, s22, 4, v0
	v_ashrrev_i32_e32 v3, 31, v2
	v_lshlrev_b32_e32 v0, 2, v167
	v_lshlrev_b64 v[4:5], 10, v[2:3]
	v_or_b32_e32 v4, v4, v0
	v_lshlrev_b64 v[10:11], 2, v[4:5]
	v_lshl_add_u64 v[38:39], s[10:11], 0, v[10:11]
	s_mov_b32 s18, 0x400000
	v_add_co_u32_e32 v40, vcc, s18, v38
	s_mov_b32 s19, 0x800000
	s_nop 0
	v_addc_co_u32_e32 v41, vcc, 0, v39, vcc
	v_lshl_add_u64 v[26:27], s[14:15], 0, v[10:11]
	v_add_co_u32_e32 v42, vcc, s19, v38
	s_barrier
	global_load_dwordx4 v[6:9], v[26:27], off
	v_addc_co_u32_e32 v43, vcc, 0, v39, vcc
	s_mov_b32 s20, 0xc00000
	global_load_dwordx4 v[10:13], v[38:39], off
	global_load_dwordx4 v[14:17], v[40:41], off
	v_add_co_u32_e32 v44, vcc, s20, v38
	global_load_dwordx4 v[18:21], v[42:43], off
	s_nop 0
	v_addc_co_u32_e32 v45, vcc, 0, v39, vcc
	global_load_dwordx4 v[22:25], v[44:45], off
	v_mov_b32_e32 v31, v5
	v_lshl_add_u64 v[28:29], v[4:5], 1, s[12:13]
	v_or_b32_e32 v30, 0x100, v4
	v_lshl_add_u64 v[32:33], v[30:31], 2, s[14:15]
	v_mov_b32_e32 v35, v5
	v_or_b32_e32 v34, 0x200, v4
	v_lshl_add_u64 v[30:31], v[30:31], 1, s[12:13]
	v_lshl_add_u64 v[36:37], v[34:35], 2, s[14:15]
	v_or_b32_e32 v4, 0x300, v4
	v_lshl_add_u64 v[34:35], v[34:35], 1, s[12:13]
	v_lshl_add_u64 v[46:47], v[4:5], 2, s[14:15]
	v_mov_b32_e32 v1, 0
	s_mov_b64 s[16:17], 0x100000
	v_cmp_gt_u32_e64 s[6:7], 16, v167
	v_cmp_eq_u32_e32 vcc, 0, v167
	v_lshl_add_u64 v[4:5], v[4:5], 1, s[12:13]
	global_load_dwordx4 v[186:189], v[32:33], off
	global_load_dwordx4 v[190:193], v[38:39], off offset:1024
	global_load_dwordx4 v[194:197], v[40:41], off offset:1024
	global_load_dwordx4 v[198:201], v[42:43], off offset:1024
	global_load_dwordx4 v[202:205], v[44:45], off offset:1024
	global_load_dwordx4 v[206:209], v[36:37], off
	global_load_dwordx4 v[210:213], v[38:39], off offset:2048
	global_load_dwordx4 v[214:217], v[40:41], off offset:2048
	global_load_dwordx4 v[218:221], v[42:43], off offset:2048
	global_load_dwordx4 v[222:225], v[44:45], off offset:2048
	global_load_dwordx4 v[226:229], v[46:47], off
	global_load_dwordx4 v[232:235], v[38:39], off offset:3072
	global_load_dwordx4 v[236:239], v[40:41], off offset:3072
	global_load_dwordx4 v[240:243], v[42:43], off offset:3072
	global_load_dwordx4 v[244:247], v[44:45], off offset:3072
	s_waitcnt vmcnt(18)
	v_pk_add_f32 v[8:9], v[8:9], v[12:13]
	v_pk_add_f32 v[6:7], v[6:7], v[10:11]
	s_waitcnt vmcnt(17)
	v_pk_add_f32 v[8:9], v[8:9], v[16:17]
	v_pk_add_f32 v[6:7], v[6:7], v[14:15]
	s_waitcnt vmcnt(16)
	v_pk_add_f32 v[8:9], v[8:9], v[20:21]
	v_pk_add_f32 v[6:7], v[6:7], v[18:19]
	s_waitcnt vmcnt(15)
	v_pk_add_f32 v[8:9], v[8:9], v[24:25]
	v_pk_add_f32 v[6:7], v[6:7], v[22:23]
	global_store_dwordx4 v[26:27], v[6:9], off
	v_cvt_pk_bf16_f32 v10, v6, v7
	v_cvt_pk_bf16_f32 v11, v8, v9
	global_store_dwordx2 v[28:29], v[10:11], off
	s_nop 0
	v_mul_f32_e32 v7, v7, v7
	v_mul_f32_e32 v9, v9, v9
	v_fmac_f32_e32 v7, v6, v6
	v_fmac_f32_e32 v9, v8, v8
	v_add_f32_e32 v6, v7, v9
	s_waitcnt vmcnt(12)
	v_mov_b32_e32 v10, v186
	v_mov_b32_e32 v11, v187
	v_mov_b32_e32 v12, v188
	v_mov_b32_e32 v13, v189
	v_mov_b32_e32 v14, v190
	v_mov_b32_e32 v15, v191
	v_mov_b32_e32 v16, v192
	v_mov_b32_e32 v17, v193
	v_mov_b32_e32 v18, v194
	v_mov_b32_e32 v19, v195
	v_mov_b32_e32 v20, v196
	v_mov_b32_e32 v21, v197
	v_mov_b32_e32 v22, v198
	v_mov_b32_e32 v23, v199
	v_mov_b32_e32 v24, v200
	v_mov_b32_e32 v25, v201
	v_mov_b32_e32 v26, v202
	v_mov_b32_e32 v27, v203
	v_mov_b32_e32 v28, v204
	v_mov_b32_e32 v29, v205
	v_pk_add_f32 v[12:13], v[12:13], v[16:17]
	v_pk_add_f32 v[10:11], v[10:11], v[14:15]
	v_pk_add_f32 v[12:13], v[12:13], v[20:21]
	v_pk_add_f32 v[10:11], v[10:11], v[18:19]
	v_pk_add_f32 v[12:13], v[12:13], v[24:25]
	v_pk_add_f32 v[10:11], v[10:11], v[22:23]
	v_pk_add_f32 v[12:13], v[12:13], v[28:29]
	v_pk_add_f32 v[10:11], v[10:11], v[26:27]
	global_store_dwordx4 v[32:33], v[10:13], off
	v_cvt_pk_bf16_f32 v14, v10, v11
	v_cvt_pk_bf16_f32 v15, v12, v13
	global_store_dwordx2 v[30:31], v[14:15], off
	s_nop 0
	v_mul_f32_e32 v7, v11, v11
	v_mul_f32_e32 v8, v13, v13
	v_fmac_f32_e32 v7, v10, v10
	v_fmac_f32_e32 v8, v12, v12
	v_add_f32_e32 v7, v7, v8
	v_add_f32_e32 v6, v6, v7
	s_waitcnt vmcnt(9)
	v_mov_b32_e32 v14, v206
	v_mov_b32_e32 v15, v207
	v_mov_b32_e32 v16, v208
	v_mov_b32_e32 v17, v209
	v_mov_b32_e32 v18, v210
	v_mov_b32_e32 v19, v211
	v_mov_b32_e32 v20, v212
	v_mov_b32_e32 v21, v213
	v_mov_b32_e32 v22, v214
	v_mov_b32_e32 v23, v215
	v_mov_b32_e32 v24, v216
	v_mov_b32_e32 v25, v217
	v_mov_b32_e32 v26, v218
	v_mov_b32_e32 v27, v219
	v_mov_b32_e32 v28, v220
	v_mov_b32_e32 v29, v221
	v_mov_b32_e32 v30, v222
	v_mov_b32_e32 v31, v223
	v_mov_b32_e32 v32, v224
	v_mov_b32_e32 v33, v225
	v_pk_add_f32 v[16:17], v[16:17], v[20:21]
	v_pk_add_f32 v[14:15], v[14:15], v[18:19]
	v_pk_add_f32 v[16:17], v[16:17], v[24:25]
	v_pk_add_f32 v[14:15], v[14:15], v[22:23]
	v_pk_add_f32 v[16:17], v[16:17], v[28:29]
	v_pk_add_f32 v[14:15], v[14:15], v[26:27]
	v_pk_add_f32 v[16:17], v[16:17], v[32:33]
	v_pk_add_f32 v[14:15], v[14:15], v[30:31]
	global_store_dwordx4 v[36:37], v[14:17], off
	v_cvt_pk_bf16_f32 v18, v14, v15
	v_cvt_pk_bf16_f32 v19, v16, v17
	global_store_dwordx2 v[34:35], v[18:19], off
	s_nop 0
	v_mul_f32_e32 v7, v15, v15
	v_mul_f32_e32 v8, v17, v17
	v_fmac_f32_e32 v7, v14, v14
	v_fmac_f32_e32 v8, v16, v16
	v_add_f32_e32 v7, v7, v8
	v_add_f32_e32 v10, v6, v7
	v_mbcnt_hi_u32_b32 v40, -1, v168
	v_lshl_add_u64 v[38:39], s[8:9], 0, v[0:1]
	v_and_b32_e32 v1, 64, v40
	v_xor_b32_e32 v41, 32, v40
	v_add_u32_e32 v43, 64, v1
	v_cmp_lt_i32_e64 s[8:9], v41, v43
	v_xor_b32_e32 v42, 16, v40
	v_xor_b32_e32 v11, 2, v40
	v_cndmask_b32_e64 v1, v40, v41, s[8:9]
	v_lshlrev_b32_e32 v1, 2, v1
	v_cmp_lt_i32_e64 s[8:9], v42, v43
	v_xor_b32_e32 v12, 1, v40
	s_waitcnt vmcnt(6)
; __device__ __forceinline__ unsigned pk2(float lo, float hi) { unsigned r; asm volatile("v_cvt_pk_bf16_f32 %0, %1, %2" : "=v"(r) : "v"(lo), "v"(hi)); return r; }
;     ...
;         for (int rr = 0; rr < 2; ++rr) {
;             const int row = rbase + rr; float sq = 0.f;
; #pragma unroll
;             for (int i = 0; i < 4; ++i) {
;                 const size_t o = (size_t)row * DM + i * 256 + lane * 4;
;                 f32x4 v = *(const f32x4*)(xold + o);
; #pragma unroll
;                 for (int q = 0; q < 4; ++q) v += *(const f32x4*)(part + (size_t)q * 1024 * DM + o);
;                 *(f32x4*)(xf_s + o) = v;
;                 u32x2 w; w.x = pk2(v[0], v[1]); w.y = pk2(v[2], v[3]); *(u32x2*)(xb_s + o) = w;
;                 sq += (v[0] * v[0] + v[1] * v[1]) + (v[2] * v[2] + v[3] * v[3]);
;             }
; #pragma unroll
;             for (int o = 32; o >= 1; o >>= 1) sq += __shfl_xor(sq, o);
;             if (lane < 16) ssq_s[(size_t)row * 16 + lane] = lane == 0 ? sq : 0.f;
;         }
	v_mov_b32_e32 v18, v226
	v_mov_b32_e32 v19, v227
	v_mov_b32_e32 v20, v228
	v_mov_b32_e32 v21, v229
	v_mov_b32_e32 v22, v232
	v_mov_b32_e32 v23, v233
	v_mov_b32_e32 v24, v234
	v_mov_b32_e32 v25, v235
	v_mov_b32_e32 v26, v236
	v_mov_b32_e32 v27, v237
	v_mov_b32_e32 v28, v238
	v_mov_b32_e32 v29, v239
	v_mov_b32_e32 v30, v240
	v_mov_b32_e32 v31, v241
	v_mov_b32_e32 v32, v242
	v_mov_b32_e32 v33, v243
	v_mov_b32_e32 v34, v244
	v_mov_b32_e32 v35, v245
	v_mov_b32_e32 v36, v246
	v_mov_b32_e32 v37, v247
	v_pk_add_f32 v[6:7], v[20:21], v[24:25]
	v_pk_add_f32 v[8:9], v[18:19], v[22:23]
	v_pk_add_f32 v[6:7], v[6:7], v[28:29]
	v_pk_add_f32 v[8:9], v[8:9], v[26:27]
	v_pk_add_f32 v[6:7], v[6:7], v[32:33]
	v_pk_add_f32 v[8:9], v[8:9], v[30:31]
	v_pk_add_f32 v[18:19], v[6:7], v[36:37]
	v_pk_add_f32 v[16:17], v[8:9], v[34:35]
	v_mul_f32_e32 v7, v19, v19
	v_mul_f32_e32 v6, v17, v17
	v_fmac_f32_e32 v6, v16, v16
	v_fmac_f32_e32 v7, v18, v18
	v_add_f32_e32 v6, v6, v7
	v_add_f32_e32 v6, v10, v6
	ds_bpermute_b32 v7, v1, v6
	v_cndmask_b32_e64 v8, v40, v42, s[8:9]
	v_lshlrev_b32_e32 v8, 2, v8
	v_xor_b32_e32 v9, 8, v40
	v_cmp_lt_i32_e64 s[8:9], v9, v43
	s_waitcnt lgkmcnt(0)
	v_add_f32_e32 v6, v6, v7
	ds_bpermute_b32 v7, v8, v6
	v_cndmask_b32_e64 v9, v40, v9, s[8:9]
	v_lshlrev_b32_e32 v9, 2, v9
	v_xor_b32_e32 v10, 4, v40
	v_cmp_lt_i32_e64 s[8:9], v10, v43
	s_waitcnt lgkmcnt(0)
	v_add_f32_e32 v6, v6, v7
	ds_bpermute_b32 v7, v9, v6
	v_cndmask_b32_e64 v10, v40, v10, s[8:9]
	v_lshlrev_b32_e32 v10, 2, v10
	v_cmp_lt_i32_e64 s[8:9], v11, v43
	global_store_dwordx4 v[46:47], v[16:19], off
	s_waitcnt lgkmcnt(0)
	v_add_f32_e32 v6, v6, v7
	ds_bpermute_b32 v7, v10, v6
	v_cndmask_b32_e64 v11, v40, v11, s[8:9]
	v_lshlrev_b32_e32 v11, 2, v11
	v_cmp_lt_i32_e64 s[8:9], v12, v43
	v_cvt_pk_bf16_f32 v16, v16, v17
	s_waitcnt lgkmcnt(0)
	v_add_f32_e32 v13, v6, v7
	ds_bpermute_b32 v14, v11, v13
	v_cndmask_b32_e64 v12, v40, v12, s[8:9]
	v_lshlrev_b32_e32 v12, 2, v12
	v_lshl_add_u64 v[6:7], v[38:39], 0, s[16:17]
	v_cvt_pk_bf16_f32 v17, v18, v19
	s_waitcnt lgkmcnt(0)
	v_add_f32_e32 v13, v13, v14
	ds_bpermute_b32 v14, v12, v13
	global_store_dwordx2 v[4:5], v[16:17], off
	s_and_saveexec_b64 s[8:9], s[6:7]
	s_cbranch_execz .LBB0_2264
	v_lshlrev_b64 v[4:5], 6, v[2:3]
	s_waitcnt lgkmcnt(0)
	v_add_f32_e32 v3, v13, v14
	v_lshl_add_u64 v[4:5], v[6:7], 0, v[4:5]
	v_cndmask_b32_e32 v3, 0, v3, vcc
	global_store_dword v[4:5], v3, off
.LBB0_2264:
	s_or_b64 exec, exec, s[8:9]
	v_or_b32_e32 v2, 1, v2
	v_ashrrev_i32_e32 v3, 31, v2
	v_lshlrev_b64 v[4:5], 10, v[2:3]
	v_or_b32_e32 v4, v4, v0
	v_lshlrev_b64 v[18:19], 2, v[4:5]
	v_lshl_add_u64 v[46:47], s[10:11], 0, v[18:19]
	v_add_co_u32_e64 v48, s[8:9], s18, v46
	v_lshl_add_u64 v[34:35], s[14:15], 0, v[18:19]
	s_nop 0
	v_addc_co_u32_e64 v49, s[8:9], 0, v47, s[8:9]
	v_add_co_u32_e64 v50, s[8:9], s19, v46
	s_waitcnt lgkmcnt(0)
	global_load_dwordx4 v[14:17], v[34:35], off
	v_addc_co_u32_e64 v51, s[8:9], 0, v47, s[8:9]
	global_load_dwordx4 v[18:21], v[46:47], off
	global_load_dwordx4 v[22:25], v[48:49], off
	v_add_co_u32_e64 v52, s[8:9], s20, v46
	global_load_dwordx4 v[26:29], v[50:51], off
	s_nop 0
	v_addc_co_u32_e64 v53, s[8:9], 0, v47, s[8:9]
	global_load_dwordx4 v[30:33], v[52:53], off
	v_mov_b32_e32 v39, v5
	v_lshl_add_u64 v[36:37], v[4:5], 1, s[12:13]
	v_or_b32_e32 v38, 0x100, v4
	v_lshl_add_u64 v[40:41], v[38:39], 2, s[14:15]
	v_mov_b32_e32 v43, v5
	v_or_b32_e32 v42, 0x200, v4
	v_lshl_add_u64 v[38:39], v[38:39], 1, s[12:13]
	v_lshl_add_u64 v[44:45], v[42:43], 2, s[14:15]
	v_or_b32_e32 v4, 0x300, v4
	v_lshl_add_u64 v[42:43], v[42:43], 1, s[12:13]
	v_lshl_add_u64 v[54:55], v[4:5], 2, s[14:15]
	v_lshl_add_u64 v[4:5], v[4:5], 1, s[12:13]
	global_load_dwordx4 v[186:189], v[40:41], off
	global_load_dwordx4 v[190:193], v[46:47], off offset:1024
	global_load_dwordx4 v[194:197], v[48:49], off offset:1024
	global_load_dwordx4 v[198:201], v[50:51], off offset:1024
	global_load_dwordx4 v[202:205], v[52:53], off offset:1024
	global_load_dwordx4 v[206:209], v[44:45], off
	global_load_dwordx4 v[210:213], v[46:47], off offset:2048
	global_load_dwordx4 v[214:217], v[48:49], off offset:2048
	global_load_dwordx4 v[218:221], v[50:51], off offset:2048
	global_load_dwordx4 v[222:225], v[52:53], off offset:2048
	global_load_dwordx4 v[226:229], v[54:55], off
	global_load_dwordx4 v[232:235], v[46:47], off offset:3072
	global_load_dwordx4 v[236:239], v[48:49], off offset:3072
	global_load_dwordx4 v[240:243], v[50:51], off offset:3072
	global_load_dwordx4 v[244:247], v[52:53], off offset:3072
	s_waitcnt vmcnt(18)
	v_pk_add_f32 v[16:17], v[16:17], v[20:21]
	v_pk_add_f32 v[14:15], v[14:15], v[18:19]
	s_waitcnt vmcnt(17)
	v_pk_add_f32 v[16:17], v[16:17], v[24:25]
	v_pk_add_f32 v[14:15], v[14:15], v[22:23]
	s_waitcnt vmcnt(16)
; __device__ __forceinline__ unsigned pk2(float lo, float hi) { unsigned r; asm volatile("v_cvt_pk_bf16_f32 %0, %1, %2" : "=v"(r) : "v"(lo), "v"(hi)); return r; }
;     ...
;             for (int i = 0; i < 4; ++i) {
;                 const size_t o = (size_t)row * DM + i * 256 + lane * 4;
;                 f32x4 v = *(const f32x4*)(xold + o);
; #pragma unroll
;                 for (int q = 0; q < 4; ++q) v += *(const f32x4*)(part + (size_t)q * 1024 * DM + o);
;                 *(f32x4*)(xf_s + o) = v;
;                 u32x2 w; w.x = pk2(v[0], v[1]); w.y = pk2(v[2], v[3]); *(u32x2*)(xb_s + o) = w;
;                 sq += (v[0] * v[0] + v[1] * v[1]) + (v[2] * v[2] + v[3] * v[3]);
;             }
; #pragma unroll
;             for (int o = 32; o >= 1; o >>= 1) sq += __shfl_xor(sq, o);
;             if (lane < 16) ssq_s[(size_t)row * 16 + lane] = lane == 0 ? sq : 0.f;
;         }
	v_pk_add_f32 v[16:17], v[16:17], v[28:29]
	v_pk_add_f32 v[14:15], v[14:15], v[26:27]
	s_waitcnt vmcnt(15)
	v_pk_add_f32 v[16:17], v[16:17], v[32:33]
	v_pk_add_f32 v[14:15], v[14:15], v[30:31]
	global_store_dwordx4 v[34:35], v[14:17], off
	v_cvt_pk_bf16_f32 v18, v14, v15
	v_cvt_pk_bf16_f32 v19, v16, v17
	global_store_dwordx2 v[36:37], v[18:19], off
	s_nop 0
	v_mul_f32_e32 v0, v15, v15
	v_mul_f32_e32 v13, v17, v17
	v_fmac_f32_e32 v0, v14, v14
	v_fmac_f32_e32 v13, v16, v16
	v_add_f32_e32 v0, v0, v13
	s_waitcnt vmcnt(12)
	v_mov_b32_e32 v18, v186
	v_mov_b32_e32 v19, v187
	v_mov_b32_e32 v20, v188
	v_mov_b32_e32 v21, v189
	v_mov_b32_e32 v22, v190
	v_mov_b32_e32 v23, v191
	v_mov_b32_e32 v24, v192
	v_mov_b32_e32 v25, v193
	v_mov_b32_e32 v26, v194
	v_mov_b32_e32 v27, v195
	v_mov_b32_e32 v28, v196
	v_mov_b32_e32 v29, v197
	v_mov_b32_e32 v30, v198
	v_mov_b32_e32 v31, v199
	v_mov_b32_e32 v32, v200
	v_mov_b32_e32 v33, v201
	v_mov_b32_e32 v34, v202
	v_mov_b32_e32 v35, v203
	v_mov_b32_e32 v36, v204
	v_mov_b32_e32 v37, v205
	v_pk_add_f32 v[20:21], v[20:21], v[24:25]
	v_pk_add_f32 v[18:19], v[18:19], v[22:23]
	v_pk_add_f32 v[20:21], v[20:21], v[28:29]
	v_pk_add_f32 v[18:19], v[18:19], v[26:27]
	v_pk_add_f32 v[20:21], v[20:21], v[32:33]
	v_pk_add_f32 v[18:19], v[18:19], v[30:31]
	v_pk_add_f32 v[20:21], v[20:21], v[36:37]
	v_pk_add_f32 v[18:19], v[18:19], v[34:35]
	global_store_dwordx4 v[40:41], v[18:21], off
	v_cvt_pk_bf16_f32 v22, v18, v19
	v_cvt_pk_bf16_f32 v23, v20, v21
	global_store_dwordx2 v[38:39], v[22:23], off
	s_nop 0
	v_mul_f32_e32 v13, v19, v19
	v_mul_f32_e32 v14, v21, v21
	v_fmac_f32_e32 v13, v18, v18
	v_fmac_f32_e32 v14, v20, v20
	v_add_f32_e32 v13, v13, v14
	v_add_f32_e32 v0, v0, v13
	s_waitcnt vmcnt(9)
	v_mov_b32_e32 v22, v206
	v_mov_b32_e32 v23, v207
	v_mov_b32_e32 v24, v208
	v_mov_b32_e32 v25, v209
	v_mov_b32_e32 v26, v210
	v_mov_b32_e32 v27, v211
	v_mov_b32_e32 v28, v212
	v_mov_b32_e32 v29, v213
	v_mov_b32_e32 v30, v214
	v_mov_b32_e32 v31, v215
	v_mov_b32_e32 v32, v216
	v_mov_b32_e32 v33, v217
	v_mov_b32_e32 v34, v218
	v_mov_b32_e32 v35, v219
	v_mov_b32_e32 v36, v220
	v_mov_b32_e32 v37, v221
	v_mov_b32_e32 v38, v222
	v_mov_b32_e32 v39, v223
	v_mov_b32_e32 v40, v224
	v_mov_b32_e32 v41, v225
	v_pk_add_f32 v[24:25], v[24:25], v[28:29]
	v_pk_add_f32 v[22:23], v[22:23], v[26:27]
	v_pk_add_f32 v[24:25], v[24:25], v[32:33]
	v_pk_add_f32 v[22:23], v[22:23], v[30:31]
	v_pk_add_f32 v[24:25], v[24:25], v[36:37]
	v_pk_add_f32 v[22:23], v[22:23], v[34:35]
	v_pk_add_f32 v[24:25], v[24:25], v[40:41]
	v_pk_add_f32 v[22:23], v[22:23], v[38:39]
	global_store_dwordx4 v[44:45], v[22:25], off
	v_cvt_pk_bf16_f32 v26, v22, v23
	v_cvt_pk_bf16_f32 v27, v24, v25
	global_store_dwordx2 v[42:43], v[26:27], off
	s_nop 0
	v_mul_f32_e32 v13, v23, v23
	v_mul_f32_e32 v14, v25, v25
	v_fmac_f32_e32 v13, v22, v22
	v_fmac_f32_e32 v14, v24, v24
	v_add_f32_e32 v13, v13, v14
	v_add_f32_e32 v0, v0, v13
	s_waitcnt vmcnt(6)
	v_mov_b32_e32 v26, v226
	v_mov_b32_e32 v27, v227
	v_mov_b32_e32 v28, v228
	v_mov_b32_e32 v29, v229
	v_mov_b32_e32 v30, v232
	v_mov_b32_e32 v31, v233
	v_mov_b32_e32 v32, v234
	v_mov_b32_e32 v33, v235
	v_mov_b32_e32 v34, v236
	v_mov_b32_e32 v35, v237
	v_mov_b32_e32 v36, v238
	v_mov_b32_e32 v37, v239
	v_mov_b32_e32 v38, v240
	v_mov_b32_e32 v39, v241
	v_mov_b32_e32 v40, v242
	v_mov_b32_e32 v41, v243
	v_mov_b32_e32 v42, v244
	v_mov_b32_e32 v43, v245
	v_mov_b32_e32 v44, v246
	v_mov_b32_e32 v45, v247
	v_pk_add_f32 v[14:15], v[28:29], v[32:33]
	v_pk_add_f32 v[16:17], v[26:27], v[30:31]
	v_pk_add_f32 v[14:15], v[14:15], v[36:37]
	v_pk_add_f32 v[16:17], v[16:17], v[34:35]
	v_pk_add_f32 v[14:15], v[14:15], v[40:41]
	v_pk_add_f32 v[18:19], v[16:17], v[38:39]
	v_pk_add_f32 v[16:17], v[14:15], v[44:45]
	v_pk_add_f32 v[14:15], v[18:19], v[42:43]
	v_mul_f32_e32 v18, v17, v17
	v_mul_f32_e32 v13, v15, v15
	v_fmac_f32_e32 v13, v14, v14
	v_fmac_f32_e32 v18, v16, v16
	v_add_f32_e32 v13, v13, v18
	v_add_f32_e32 v0, v0, v13
	ds_bpermute_b32 v1, v1, v0
	global_store_dwordx4 v[54:55], v[14:17], off
	s_waitcnt lgkmcnt(0)
	v_add_f32_e32 v0, v0, v1
	ds_bpermute_b32 v1, v8, v0
	v_cvt_pk_bf16_f32 v8, v14, v15
	s_waitcnt lgkmcnt(0)
	v_add_f32_e32 v0, v0, v1
	ds_bpermute_b32 v1, v9, v0
	v_cvt_pk_bf16_f32 v9, v16, v17
	global_store_dwordx2 v[4:5], v[8:9], off
	s_waitcnt lgkmcnt(0)
	v_add_f32_e32 v0, v0, v1
	ds_bpermute_b32 v1, v10, v0
	s_waitcnt lgkmcnt(0)
	v_add_f32_e32 v0, v0, v1
	ds_bpermute_b32 v1, v11, v0
	s_waitcnt lgkmcnt(0)
	v_add_f32_e32 v0, v0, v1
	ds_bpermute_b32 v1, v12, v0
	s_and_saveexec_b64 s[8:9], s[6:7]
	s_cbranch_execz .LBB0_2266
	v_lshlrev_b64 v[2:3], 6, v[2:3]
	s_waitcnt lgkmcnt(0)
	v_add_f32_e32 v0, v0, v1
	v_lshl_add_u64 v[2:3], v[6:7], 0, v[2:3]
	v_cndmask_b32_e32 v0, 0, v0, vcc
	global_store_dword v[2:3], v0, off
